# c8 plus peeled first K-iteration with C=0 first-touch MFMAs in the four multi-unit GEMM loops (no accumulator clears)
# baseline (speedup 1.0000x reference)
; __device__ __forceinline__ const char* b_base(const Gemm& g, const Unit& u) { return (const char*)g.Bt + (size_t)u.pn * 2 * (g.K >> 6) * BLK; }
; #define PG8_STAGE(bufoff, gbase, voff) do { _Pragma("unroll") for (int _i = 0; _i < 2; ++_i) \
;         __builtin_amdgcn_global_load_lds((const unsigned*)((const char*)(gbase) + (voff)[_i]), (LAS unsigned*)(lds + (bufoff) + ldsw + _i * 8192), 16, 0, 0); } while (0)
; #define PG8_LDA(dst, b, h) do { _Pragma("unroll") for (int m = 0; m < 4; ++m) _Pragma("unroll") for (int k = 0; k < 2; ++k) dst[m][k] = *(const LAS bf16x8*)(lds + PG8_SA(b, h) + aoff + m * 2048 + k * 1024); } while (0)
; #define PG8_LDB(dst, b, h) do { _Pragma("unroll") for (int n = 0; n < 2; ++n) _Pragma("unroll") for (int k = 0; k < 2; ++k) dst[n][k] = *(const LAS bf16x8*)(lds + PG8_SB(b, h) + boff + n * 2048 + k * 1024); } while (0)
; #define PG8_BAR __builtin_amdgcn_s_barrier()
; template <class Epi, bool ALIGN_EPI = true, bool SP2 = true>
; __device__ __forceinline__ void gemm_phase(LAS unsigned char* lds, const Gemm g, const StaticOrder& S, const Epi& E, unsigned long long& tacc, const int tmode) {
;     ...
;         const bool has_next = S.next(ui + 1, nxt);
;         const char* nA = has_next ? a_base(g, nxt) : cA; const char* nB = has_next ? b_base(g, nxt) : cB;
;         unsigned long long tk0 = 0ull; if (tmode == 1) tk0 = __builtin_amdgcn_s_memrealtime(); if (tmode == 3) tk0 = (unsigned long long)clock64();
; #pragma unroll 1
;         for (int t = 0; t < nt; t += 2) {
;             const bool last = (t == nt - 2);
;             const char* a1 = cA + (size_t)(t + 1) * kstepA;
;             const char* a2 = last ? nA : cA + (size_t)(t + 2) * kstepA; const char* b2 = last ? nB : cB + (size_t)(t + 2) * kstepB;
;             const char* a3 = a2 + kstepA; const char* b3 = b2 + kstepB;
;             if constexpr (SP2) {
;             PG8_LDB(B0, 0, 0); PG8_LDB(B1, 0, 1); PG8_SCHED; PG8_LDA(At, 0, 0); PG8_STAGE(PG8_SA(1, 1), a1 + hstepA, voffA);
;             PG8_WAIT_V(8); PG8_WAIT_L(0); PG8_BAR; PG8_MMA(0, 0, At, B0); PG8_MMA(0, 1, At, B1); PG8_BAR; PG8_SCHED;
;             PG8_LDA(At, 0, 1); PG8_STAGE(PG8_SB(0, 0), b2, voffB); PG8_STAGE(PG8_SB(0, 1), b2 + hstepB, voffB); PG8_STAGE(PG8_SA(0, 0), a2, voffA);
;             PG8_WAIT_V(8); PG8_WAIT_L(0); PG8_BAR; PG8_MMA(1, 0, At, B0); PG8_MMA(1, 1, At, B1); PG8_BAR; PG8_SCHED;
.LBB0_132:
	s_ashr_i32 s25, s24, 31
	s_lshl_b64 s[0:1], s[24:25], 20
	v_readlane_b32 s26, v255, 9
	v_readlane_b32 s27, v255, 10
	s_add_u32 s26, s26, s0
	s_addc_u32 s27, s27, s1
	s_and_b64 s[0:1], s[36:37], exec
	s_cselect_b32 s25, s27, s23
	s_cselect_b32 s50, s26, s22
	s_ashr_i32 s21, s20, 31
	s_lshl_b64 s[0:1], s[20:21], 20
	v_readlane_b32 s21, v254, 6
	s_add_u32 s28, s21, s0
	v_readlane_b32 s0, v254, 7
	s_addc_u32 s29, s0, s1
	s_and_b64 s[0:1], s[36:37], exec
	s_cselect_b32 s21, s29, s31
	s_cselect_b32 s51, s28, s30
	s_add_u32 s22, s22, 0x84000
	s_addc_u32 s23, s23, 0
	s_add_u32 s54, s30, 0x8000
	v_mov_b32_e32 v2, 0
	s_addc_u32 s55, s31, 0
	s_mov_b32 s56, -2
	s_add_u32 s0, s22, 0xfff84000
	s_addc_u32 s1, s23, -1
	s_cmp_eq_u32 s56, 28
	s_cselect_b32 s34, s50, s0
	s_cselect_b32 s35, s25, s1
	s_cselect_b32 s38, s51, s54
	s_cselect_b32 s39, s21, s55
	s_add_u32 s30, s34, 0x4000
	s_addc_u32 s31, s35, 0
	s_add_i32 s0, 0, 0x10000
	v_add_u32_e32 v141, s0, v139
	s_add_i32 s33, 0, 0x14000
	ds_read_b128 v[134:137], v141
	ds_read_b128 v[142:145], v141 offset:1024
	ds_read_b128 v[146:149], v141 offset:2048
	ds_read_b128 v[150:153], v141 offset:3072
	v_add_u32_e32 v141, s33, v139
	ds_read_b128 v[154:157], v141
	ds_read_b128 v[158:161], v141 offset:1024
	ds_read_b128 v[162:165], v141 offset:2048
	ds_read_b128 v[166:169], v141 offset:3072
	v_lshl_add_u64 v[190:191], s[22:23], 0, v[130:131]
	s_add_i32 m0, s10, 0xc000
	ds_read_b128 v[170:173], v140
	ds_read_b128 v[174:177], v140 offset:1024
	ds_read_b128 v[178:181], v140 offset:2048
	ds_read_b128 v[182:185], v140 offset:3072
	ds_read_b128 v[186:189], v140 offset:4096
	ds_read_b128 v[194:197], v140 offset:5120
	ds_read_b128 v[206:209], v140 offset:6144
	ds_read_b128 v[210:213], v140 offset:7168
	global_load_lds_dwordx4 v[190:191], off
	v_lshl_add_u64 v[190:191], s[22:23], 0, v[132:133]
	s_add_i32 m0, s10, 0xe000
	s_nop 0
	global_load_lds_dwordx4 v[190:191], off
	s_waitcnt vmcnt(8)
	s_waitcnt lgkmcnt(0)
	s_barrier
	s_setprio 1
	s_waitcnt lgkmcnt(0)
	v_mfma_f32_16x16x32_bf16 v[126:129], v[134:137], v[170:173], 0
	v_mfma_f32_16x16x32_bf16 v[122:125], v[146:149], v[170:173], 0
	v_mfma_f32_16x16x32_bf16 v[110:113], v[134:137], v[178:181], 0
	v_mfma_f32_16x16x32_bf16 v[106:109], v[146:149], v[178:181], 0
	v_mfma_f32_16x16x32_bf16 v[94:97], v[134:137], v[186:189], 0
	v_mfma_f32_16x16x32_bf16 v[90:93], v[146:149], v[186:189], 0
	v_mfma_f32_16x16x32_bf16 v[78:81], v[134:137], v[206:209], 0
	v_mfma_f32_16x16x32_bf16 v[74:77], v[146:149], v[206:209], 0
	v_mfma_f32_16x16x32_bf16 v[126:129], v[142:145], v[174:177], v[126:129]
	v_mfma_f32_16x16x32_bf16 v[122:125], v[150:153], v[174:177], v[122:125]
	v_mfma_f32_16x16x32_bf16 v[110:113], v[142:145], v[182:185], v[110:113]
	v_mfma_f32_16x16x32_bf16 v[106:109], v[150:153], v[182:185], v[106:109]
	v_mfma_f32_16x16x32_bf16 v[94:97], v[142:145], v[194:197], v[94:97]
	v_mfma_f32_16x16x32_bf16 v[90:93], v[150:153], v[194:197], v[90:93]
	v_mfma_f32_16x16x32_bf16 v[78:81], v[142:145], v[210:213], v[78:81]
	v_mfma_f32_16x16x32_bf16 v[74:77], v[150:153], v[210:213], v[74:77]
	s_setprio 0
	s_setprio 1
	v_mfma_f32_16x16x32_bf16 v[118:121], v[154:157], v[170:173], 0
	v_mfma_f32_16x16x32_bf16 v[114:117], v[162:165], v[170:173], 0
	v_mfma_f32_16x16x32_bf16 v[102:105], v[154:157], v[178:181], 0
	v_mfma_f32_16x16x32_bf16 v[98:101], v[162:165], v[178:181], 0
	v_mfma_f32_16x16x32_bf16 v[86:89], v[154:157], v[186:189], 0
	v_mfma_f32_16x16x32_bf16 v[82:85], v[162:165], v[186:189], 0
	v_mfma_f32_16x16x32_bf16 v[70:73], v[154:157], v[206:209], 0
	v_mfma_f32_16x16x32_bf16 v[66:69], v[162:165], v[206:209], 0
	v_mfma_f32_16x16x32_bf16 v[118:121], v[158:161], v[174:177], v[118:121]
	v_mfma_f32_16x16x32_bf16 v[114:117], v[166:169], v[174:177], v[114:117]
	v_mfma_f32_16x16x32_bf16 v[102:105], v[158:161], v[182:185], v[102:105]
	v_mfma_f32_16x16x32_bf16 v[98:101], v[166:169], v[182:185], v[98:101]
	v_mfma_f32_16x16x32_bf16 v[86:89], v[158:161], v[194:197], v[86:89]
	v_mfma_f32_16x16x32_bf16 v[82:85], v[166:169], v[194:197], v[82:85]
	v_mfma_f32_16x16x32_bf16 v[70:73], v[158:161], v[210:213], v[70:73]
	s_barrier
	v_mfma_f32_16x16x32_bf16 v[66:69], v[166:169], v[210:213], v[66:69]
	s_setprio 0
	s_add_i32 s0, s0, s2
	v_lshl_add_u64 v[190:191], s[38:39], 0, v[130:131]
	s_mov_b32 m0, s0
	ds_read_b128 v[170:173], v140 offset:16384
	ds_read_b128 v[174:177], v140 offset:17408
	ds_read_b128 v[178:181], v140 offset:18432
	ds_read_b128 v[182:185], v140 offset:19456
	ds_read_b128 v[186:189], v140 offset:20480
	ds_read_b128 v[194:197], v140 offset:21504
	ds_read_b128 v[206:209], v140 offset:22528
	ds_read_b128 v[210:213], v140 offset:23552
	global_load_lds_dwordx4 v[190:191], off
	s_add_i32 m0, s0, 0x2000
	s_add_u32 s0, s38, 0x80000
	v_lshl_add_u64 v[190:191], s[38:39], 0, v[132:133]
	s_addc_u32 s1, s39, 0
	s_add_i32 s33, s33, s2
	global_load_lds_dwordx4 v[190:191], off
	v_lshl_add_u64 v[190:191], s[0:1], 0, v[130:131]
	s_mov_b32 m0, s33
	s_nop 0
	global_load_lds_dwordx4 v[190:191], off
	v_lshl_add_u64 v[190:191], s[0:1], 0, v[132:133]
	s_add_i32 m0, s33, 0x2000
	s_nop 0
	global_load_lds_dwordx4 v[190:191], off
	v_lshl_add_u64 v[190:191], s[34:35], 0, v[130:131]
	s_mov_b32 m0, s10
	s_nop 0
	global_load_lds_dwordx4 v[190:191], off
	v_lshl_add_u64 v[190:191], s[34:35], 0, v[132:133]
	s_mov_b32 m0, s40
	s_nop 0
	global_load_lds_dwordx4 v[190:191], off
	s_waitcnt vmcnt(8)
	s_waitcnt lgkmcnt(0)
	s_barrier
; #define PG8_STAGE(bufoff, gbase, voff) do { _Pragma("unroll") for (int _i = 0; _i < 2; ++_i) \
;         __builtin_amdgcn_global_load_lds((const unsigned*)((const char*)(gbase) + (voff)[_i]), (LAS unsigned*)(lds + (bufoff) + ldsw + _i * 8192), 16, 0, 0); } while (0)
; #define PG8_LDA(dst, b, h) do { _Pragma("unroll") for (int m = 0; m < 4; ++m) _Pragma("unroll") for (int k = 0; k < 2; ++k) dst[m][k] = *(const LAS bf16x8*)(lds + PG8_SA(b, h) + aoff + m * 2048 + k * 1024); } while (0)
; #define PG8_LDB(dst, b, h) do { _Pragma("unroll") for (int n = 0; n < 2; ++n) _Pragma("unroll") for (int k = 0; k < 2; ++k) dst[n][k] = *(const LAS bf16x8*)(lds + PG8_SB(b, h) + boff + n * 2048 + k * 1024); } while (0)
; #define PG8_MMA(ai, bj, At, Bt) do { __builtin_amdgcn_s_setprio(1); _Pragma("unroll") for (int m = 0; m < 4; ++m) _Pragma("unroll") for (int n = 0; n < 2; ++n) _Pragma("unroll") for (int k = 0; k < 2; ++k) \
;         acc[ai][bj][m][n] = __builtin_amdgcn_mfma_f32_16x16x32_bf16(Bt[n][k], At[m][k], acc[ai][bj][m][n], 0, 0, 0); __builtin_amdgcn_s_setprio(0); } while (0)
; #define PG8_WAIT_V(n) asm volatile("s_waitcnt vmcnt(" #n ")" ::: "memory")
; #define PG8_WAIT_L(n) asm volatile("s_waitcnt lgkmcnt(" #n ")" ::: "memory")
; #define PG8_BAR __builtin_amdgcn_s_barrier()
; #define PG8_SCHED __builtin_amdgcn_sched_barrier(0)
; template <class Epi, bool ALIGN_EPI = true, bool SP2 = true>
; __device__ __forceinline__ void gemm_phase(LAS unsigned char* lds, const Gemm g, const StaticOrder& S, const Epi& E, unsigned long long& tacc, const int tmode) {
;     ...
;             PG8_WAIT_V(8); PG8_WAIT_L(0); PG8_BAR; PG8_MMA(1, 0, At, B0); PG8_MMA(1, 1, At, B1); PG8_BAR; PG8_SCHED;
;             PG8_LDB(B0, 1, 0); PG8_LDB(B1, 1, 1); PG8_SCHED; PG8_LDA(At, 1, 0); PG8_STAGE(PG8_SA(0, 1), a2 + hstepA, voffA);
;             PG8_WAIT_V(8); PG8_WAIT_L(0); PG8_BAR; PG8_MMA(0, 0, At, B0); PG8_MMA(0, 1, At, B1); PG8_BAR; PG8_SCHED;
	s_setprio 1
	s_waitcnt lgkmcnt(0)
	v_mfma_f32_16x16x32_bf16 v[62:65], v[134:137], v[170:173], 0
	v_mfma_f32_16x16x32_bf16 v[58:61], v[146:149], v[170:173], 0
	v_mfma_f32_16x16x32_bf16 v[46:49], v[134:137], v[178:181], 0
	v_mfma_f32_16x16x32_bf16 v[42:45], v[146:149], v[178:181], 0
	v_mfma_f32_16x16x32_bf16 v[30:33], v[134:137], v[186:189], 0
	v_mfma_f32_16x16x32_bf16 v[26:29], v[146:149], v[186:189], 0
	v_mfma_f32_16x16x32_bf16 v[14:17], v[134:137], v[206:209], 0
	v_mfma_f32_16x16x32_bf16 v[10:13], v[146:149], v[206:209], 0
	v_mfma_f32_16x16x32_bf16 v[62:65], v[142:145], v[174:177], v[62:65]
	v_mfma_f32_16x16x32_bf16 v[58:61], v[150:153], v[174:177], v[58:61]
	v_mfma_f32_16x16x32_bf16 v[46:49], v[142:145], v[182:185], v[46:49]
	v_mfma_f32_16x16x32_bf16 v[42:45], v[150:153], v[182:185], v[42:45]
	v_mfma_f32_16x16x32_bf16 v[30:33], v[142:145], v[194:197], v[30:33]
	v_mfma_f32_16x16x32_bf16 v[26:29], v[150:153], v[194:197], v[26:29]
	v_mfma_f32_16x16x32_bf16 v[14:17], v[142:145], v[210:213], v[14:17]
	v_mfma_f32_16x16x32_bf16 v[10:13], v[150:153], v[210:213], v[10:13]
	s_setprio 0
	s_setprio 1
	v_mfma_f32_16x16x32_bf16 v[54:57], v[154:157], v[170:173], 0
	v_mfma_f32_16x16x32_bf16 v[50:53], v[162:165], v[170:173], 0
	v_mfma_f32_16x16x32_bf16 v[38:41], v[154:157], v[178:181], 0
	v_mfma_f32_16x16x32_bf16 v[34:37], v[162:165], v[178:181], 0
	v_mfma_f32_16x16x32_bf16 v[22:25], v[154:157], v[186:189], 0
	v_mfma_f32_16x16x32_bf16 v[18:21], v[162:165], v[186:189], 0
	v_mfma_f32_16x16x32_bf16 v[6:9], v[154:157], v[206:209], 0
	v_mfma_f32_16x16x32_bf16 v[2:5], v[162:165], v[206:209], 0
	v_mfma_f32_16x16x32_bf16 v[54:57], v[158:161], v[174:177], v[54:57]
	v_mfma_f32_16x16x32_bf16 v[50:53], v[166:169], v[174:177], v[50:53]
	v_mfma_f32_16x16x32_bf16 v[38:41], v[158:161], v[182:185], v[38:41]
	v_mfma_f32_16x16x32_bf16 v[34:37], v[166:169], v[182:185], v[34:37]
	v_mfma_f32_16x16x32_bf16 v[22:25], v[158:161], v[194:197], v[22:25]
	v_mfma_f32_16x16x32_bf16 v[18:21], v[166:169], v[194:197], v[18:21]
	v_mfma_f32_16x16x32_bf16 v[6:9], v[158:161], v[210:213], v[6:9]
	s_barrier
	v_mfma_f32_16x16x32_bf16 v[2:5], v[166:169], v[210:213], v[2:5]
	s_setprio 0
	s_add_i32 s33, 0, 0x18000
	v_add_u32_e32 v141, s33, v139
	s_add_i32 s57, 0, 0x1c000
	ds_read_b128 v[134:137], v141
	ds_read_b128 v[142:145], v141 offset:1024
	ds_read_b128 v[146:149], v141 offset:2048
	ds_read_b128 v[150:153], v141 offset:3072
	v_add_u32_e32 v141, s57, v139
	ds_read_b128 v[154:157], v141
	ds_read_b128 v[158:161], v141 offset:1024
	ds_read_b128 v[162:165], v141 offset:2048
	ds_read_b128 v[166:169], v141 offset:3072
	s_add_u32 s0, s34, 0x80000
	s_addc_u32 s1, s35, 0
	s_mov_b32 m0, s41
	v_lshl_add_u64 v[190:191], s[0:1], 0, v[130:131]
	ds_read_b128 v[170:173], v140 offset:32768
	ds_read_b128 v[174:177], v140 offset:33792
	ds_read_b128 v[178:181], v140 offset:34816
	ds_read_b128 v[182:185], v140 offset:35840
	ds_read_b128 v[186:189], v140 offset:36864
	ds_read_b128 v[194:197], v140 offset:37888
	ds_read_b128 v[206:209], v140 offset:38912
	ds_read_b128 v[210:213], v140 offset:39936
	global_load_lds_dwordx4 v[190:191], off
	v_lshl_add_u64 v[190:191], s[0:1], 0, v[132:133]
	s_mov_b32 m0, s42
	s_nop 0
	global_load_lds_dwordx4 v[190:191], off
	s_waitcnt vmcnt(8)
	s_waitcnt lgkmcnt(0)
	s_barrier
	s_setprio 1
	s_waitcnt lgkmcnt(0)
	v_mfma_f32_16x16x32_bf16 v[126:129], v[134:137], v[170:173], v[126:129]
	v_mfma_f32_16x16x32_bf16 v[122:125], v[146:149], v[170:173], v[122:125]
	v_mfma_f32_16x16x32_bf16 v[110:113], v[134:137], v[178:181], v[110:113]
	v_mfma_f32_16x16x32_bf16 v[106:109], v[146:149], v[178:181], v[106:109]
	v_mfma_f32_16x16x32_bf16 v[94:97], v[134:137], v[186:189], v[94:97]
	v_mfma_f32_16x16x32_bf16 v[90:93], v[146:149], v[186:189], v[90:93]
	v_mfma_f32_16x16x32_bf16 v[78:81], v[134:137], v[206:209], v[78:81]
	v_mfma_f32_16x16x32_bf16 v[74:77], v[146:149], v[206:209], v[74:77]
	v_mfma_f32_16x16x32_bf16 v[126:129], v[142:145], v[174:177], v[126:129]
	v_mfma_f32_16x16x32_bf16 v[122:125], v[150:153], v[174:177], v[122:125]
	v_mfma_f32_16x16x32_bf16 v[110:113], v[142:145], v[182:185], v[110:113]
	v_mfma_f32_16x16x32_bf16 v[106:109], v[150:153], v[182:185], v[106:109]
	v_mfma_f32_16x16x32_bf16 v[94:97], v[142:145], v[194:197], v[94:97]
	v_mfma_f32_16x16x32_bf16 v[90:93], v[150:153], v[194:197], v[90:93]
	v_mfma_f32_16x16x32_bf16 v[78:81], v[142:145], v[210:213], v[78:81]
	v_mfma_f32_16x16x32_bf16 v[74:77], v[150:153], v[210:213], v[74:77]
	s_setprio 0
	s_setprio 1
	v_mfma_f32_16x16x32_bf16 v[118:121], v[154:157], v[170:173], v[118:121]
	v_mfma_f32_16x16x32_bf16 v[114:117], v[162:165], v[170:173], v[114:117]
	v_mfma_f32_16x16x32_bf16 v[102:105], v[154:157], v[178:181], v[102:105]
	v_mfma_f32_16x16x32_bf16 v[98:101], v[162:165], v[178:181], v[98:101]
	v_mfma_f32_16x16x32_bf16 v[86:89], v[154:157], v[186:189], v[86:89]
	v_mfma_f32_16x16x32_bf16 v[82:85], v[162:165], v[186:189], v[82:85]
	v_mfma_f32_16x16x32_bf16 v[70:73], v[154:157], v[206:209], v[70:73]
	v_mfma_f32_16x16x32_bf16 v[66:69], v[162:165], v[206:209], v[66:69]
	v_mfma_f32_16x16x32_bf16 v[118:121], v[158:161], v[174:177], v[118:121]
	v_mfma_f32_16x16x32_bf16 v[114:117], v[166:169], v[174:177], v[114:117]
	v_mfma_f32_16x16x32_bf16 v[102:105], v[158:161], v[182:185], v[102:105]
	v_mfma_f32_16x16x32_bf16 v[98:101], v[166:169], v[182:185], v[98:101]
	v_mfma_f32_16x16x32_bf16 v[86:89], v[158:161], v[194:197], v[86:89]
	v_mfma_f32_16x16x32_bf16 v[82:85], v[166:169], v[194:197], v[82:85]
	v_mfma_f32_16x16x32_bf16 v[70:73], v[158:161], v[210:213], v[70:73]
	s_barrier
; #define PG8_STAGE(bufoff, gbase, voff) do { _Pragma("unroll") for (int _i = 0; _i < 2; ++_i) \
;         __builtin_amdgcn_global_load_lds((const unsigned*)((const char*)(gbase) + (voff)[_i]), (LAS unsigned*)(lds + (bufoff) + ldsw + _i * 8192), 16, 0, 0); } while (0)
; #define PG8_LDA(dst, b, h) do { _Pragma("unroll") for (int m = 0; m < 4; ++m) _Pragma("unroll") for (int k = 0; k < 2; ++k) dst[m][k] = *(const LAS bf16x8*)(lds + PG8_SA(b, h) + aoff + m * 2048 + k * 1024); } while (0)
; #define PG8_MMA(ai, bj, At, Bt) do { __builtin_amdgcn_s_setprio(1); _Pragma("unroll") for (int m = 0; m < 4; ++m) _Pragma("unroll") for (int n = 0; n < 2; ++n) _Pragma("unroll") for (int k = 0; k < 2; ++k) \
;         acc[ai][bj][m][n] = __builtin_amdgcn_mfma_f32_16x16x32_bf16(Bt[n][k], At[m][k], acc[ai][bj][m][n], 0, 0, 0); __builtin_amdgcn_s_setprio(0); } while (0)
; #define PG8_WAIT_V(n) asm volatile("s_waitcnt vmcnt(" #n ")" ::: "memory")
; #define PG8_WAIT_L(n) asm volatile("s_waitcnt lgkmcnt(" #n ")" ::: "memory")
; #define PG8_BAR __builtin_amdgcn_s_barrier()
; #define PG8_SCHED __builtin_amdgcn_sched_barrier(0)
; template <class Epi, bool ALIGN_EPI = true, bool SP2 = true>
; __device__ __forceinline__ void gemm_phase(LAS unsigned char* lds, const Gemm g, const StaticOrder& S, const Epi& E, unsigned long long& tacc, const int tmode) {
;     ...
;         for (int t = 0; t < nt; t += 2) {
;             const bool last = (t == nt - 2);
;             const char* a1 = cA + (size_t)(t + 1) * kstepA;
;             const char* a2 = last ? nA : cA + (size_t)(t + 2) * kstepA; const char* b2 = last ? nB : cB + (size_t)(t + 2) * kstepB;
;             const char* a3 = a2 + kstepA; const char* b3 = b2 + kstepB;
;     ...
;             PG8_LDA(At, 1, 1); PG8_STAGE(PG8_SB(1, 0), b3, voffB); PG8_STAGE(PG8_SB(1, 1), b3 + hstepB, voffB); PG8_STAGE(PG8_SA(1, 0), a3, voffA);
;             PG8_WAIT_V(8); PG8_WAIT_L(0); PG8_BAR; PG8_MMA(1, 0, At, B0); PG8_MMA(1, 1, At, B1); PG8_BAR; PG8_SCHED;
	v_mfma_f32_16x16x32_bf16 v[66:69], v[166:169], v[210:213], v[66:69]
	s_setprio 0
	s_add_u32 s0, s38, 0x4000
	s_addc_u32 s1, s39, 0
	s_add_i32 s33, s33, s2
	v_lshl_add_u64 v[190:191], s[0:1], 0, v[130:131]
	s_mov_b32 m0, s33
	ds_read_b128 v[170:173], v140 offset:49152
	ds_read_b128 v[174:177], v140 offset:50176
	ds_read_b128 v[178:181], v140 offset:51200
	ds_read_b128 v[182:185], v140 offset:52224
	ds_read_b128 v[186:189], v140 offset:53248
	ds_read_b128 v[194:197], v140 offset:54272
	ds_read_b128 v[206:209], v140 offset:55296
	ds_read_b128 v[210:213], v140 offset:56320
	global_load_lds_dwordx4 v[190:191], off
	s_add_i32 m0, s33, 0x2000
	v_lshl_add_u64 v[190:191], s[0:1], 0, v[132:133]
	s_add_u32 s0, s38, 0x84000
	s_addc_u32 s1, s39, 0
	s_add_i32 s33, s57, s2
	global_load_lds_dwordx4 v[190:191], off
	v_lshl_add_u64 v[190:191], s[0:1], 0, v[130:131]
	s_mov_b32 m0, s33
	s_nop 0
	global_load_lds_dwordx4 v[190:191], off
	v_lshl_add_u64 v[190:191], s[0:1], 0, v[132:133]
	s_add_i32 m0, s33, 0x2000
	s_nop 0
	global_load_lds_dwordx4 v[190:191], off
	v_lshl_add_u64 v[190:191], s[30:31], 0, v[130:131]
	s_mov_b32 m0, s45
	s_nop 0
	global_load_lds_dwordx4 v[190:191], off
	v_lshl_add_u64 v[190:191], s[30:31], 0, v[132:133]
	s_mov_b32 m0, s46
	s_nop 0
	global_load_lds_dwordx4 v[190:191], off
	s_waitcnt vmcnt(8)
	s_waitcnt lgkmcnt(0)
	s_barrier
	s_setprio 1
	s_waitcnt lgkmcnt(0)
	v_mfma_f32_16x16x32_bf16 v[62:65], v[134:137], v[170:173], v[62:65]
	v_mfma_f32_16x16x32_bf16 v[58:61], v[146:149], v[170:173], v[58:61]
	v_mfma_f32_16x16x32_bf16 v[46:49], v[134:137], v[178:181], v[46:49]
	v_mfma_f32_16x16x32_bf16 v[42:45], v[146:149], v[178:181], v[42:45]
	v_mfma_f32_16x16x32_bf16 v[30:33], v[134:137], v[186:189], v[30:33]
	v_mfma_f32_16x16x32_bf16 v[26:29], v[146:149], v[186:189], v[26:29]
	v_mfma_f32_16x16x32_bf16 v[14:17], v[134:137], v[206:209], v[14:17]
	v_mfma_f32_16x16x32_bf16 v[10:13], v[146:149], v[206:209], v[10:13]
	v_mfma_f32_16x16x32_bf16 v[62:65], v[142:145], v[174:177], v[62:65]
	v_mfma_f32_16x16x32_bf16 v[58:61], v[150:153], v[174:177], v[58:61]
	v_mfma_f32_16x16x32_bf16 v[46:49], v[142:145], v[182:185], v[46:49]
	v_mfma_f32_16x16x32_bf16 v[42:45], v[150:153], v[182:185], v[42:45]
	v_mfma_f32_16x16x32_bf16 v[30:33], v[142:145], v[194:197], v[30:33]
	v_mfma_f32_16x16x32_bf16 v[26:29], v[150:153], v[194:197], v[26:29]
	v_mfma_f32_16x16x32_bf16 v[14:17], v[142:145], v[210:213], v[14:17]
	v_mfma_f32_16x16x32_bf16 v[10:13], v[150:153], v[210:213], v[10:13]
	s_setprio 0
	s_setprio 1
	v_mfma_f32_16x16x32_bf16 v[54:57], v[154:157], v[170:173], v[54:57]
	v_mfma_f32_16x16x32_bf16 v[50:53], v[162:165], v[170:173], v[50:53]
	v_mfma_f32_16x16x32_bf16 v[38:41], v[154:157], v[178:181], v[38:41]
	v_mfma_f32_16x16x32_bf16 v[34:37], v[162:165], v[178:181], v[34:37]
	v_mfma_f32_16x16x32_bf16 v[22:25], v[154:157], v[186:189], v[22:25]
	v_mfma_f32_16x16x32_bf16 v[18:21], v[162:165], v[186:189], v[18:21]
	v_mfma_f32_16x16x32_bf16 v[6:9], v[154:157], v[206:209], v[6:9]
	v_mfma_f32_16x16x32_bf16 v[2:5], v[162:165], v[206:209], v[2:5]
	v_mfma_f32_16x16x32_bf16 v[54:57], v[158:161], v[174:177], v[54:57]
	v_mfma_f32_16x16x32_bf16 v[50:53], v[166:169], v[174:177], v[50:53]
	v_mfma_f32_16x16x32_bf16 v[38:41], v[158:161], v[182:185], v[38:41]
	v_mfma_f32_16x16x32_bf16 v[34:37], v[166:169], v[182:185], v[34:37]
	v_mfma_f32_16x16x32_bf16 v[22:25], v[158:161], v[194:197], v[22:25]
	v_mfma_f32_16x16x32_bf16 v[18:21], v[166:169], v[194:197], v[18:21]
	v_mfma_f32_16x16x32_bf16 v[6:9], v[158:161], v[210:213], v[6:9]
	s_barrier
	v_mfma_f32_16x16x32_bf16 v[2:5], v[166:169], v[210:213], v[2:5]
	s_setprio 0
	s_add_i32 s56, s56, 2
	s_add_u32 s22, s22, 0x8000
	s_addc_u32 s23, s23, 0
	s_add_u32 s54, s54, 0x8000
	s_addc_u32 s55, s55, 0
	s_cmp_lt_u32 s56, 30

; __device__ __forceinline__ const char* b_base(const Gemm& g, const Unit& u) { return (const char*)g.Bt + (size_t)u.pn * 2 * (g.K >> 6) * BLK; }
; #define PG8_STAGE(bufoff, gbase, voff) do { _Pragma("unroll") for (int _i = 0; _i < 2; ++_i) \
;         __builtin_amdgcn_global_load_lds((const unsigned*)((const char*)(gbase) + (voff)[_i]), (LAS unsigned*)(lds + (bufoff) + ldsw + _i * 8192), 16, 0, 0); } while (0)
; #define PG8_LDA(dst, b, h) do { _Pragma("unroll") for (int m = 0; m < 4; ++m) _Pragma("unroll") for (int k = 0; k < 2; ++k) dst[m][k] = *(const LAS bf16x8*)(lds + PG8_SA(b, h) + aoff + m * 2048 + k * 1024); } while (0)
; #define PG8_LDB(dst, b, h) do { _Pragma("unroll") for (int n = 0; n < 2; ++n) _Pragma("unroll") for (int k = 0; k < 2; ++k) dst[n][k] = *(const LAS bf16x8*)(lds + PG8_SB(b, h) + boff + n * 2048 + k * 1024); } while (0)
; #define PG8_BAR __builtin_amdgcn_s_barrier()
; template <class Epi, bool ALIGN_EPI = true, bool SP2 = true>
; __device__ __forceinline__ void gemm_phase(LAS unsigned char* lds, const Gemm g, const StaticOrder& S, const Epi& E, unsigned long long& tacc, const int tmode) {
;     ...
;         const bool has_next = S.next(ui + 1, nxt);
;         const char* nA = has_next ? a_base(g, nxt) : cA; const char* nB = has_next ? b_base(g, nxt) : cB;
;         unsigned long long tk0 = 0ull; if (tmode == 1) tk0 = __builtin_amdgcn_s_memrealtime(); if (tmode == 3) tk0 = (unsigned long long)clock64();
; #pragma unroll 1
;         for (int t = 0; t < nt; t += 2) {
;             const bool last = (t == nt - 2);
;             const char* a1 = cA + (size_t)(t + 1) * kstepA;
;             const char* a2 = last ? nA : cA + (size_t)(t + 2) * kstepA; const char* b2 = last ? nB : cB + (size_t)(t + 2) * kstepB;
;             const char* a3 = a2 + kstepA; const char* b3 = b2 + kstepB;
;             if constexpr (SP2) {
;             PG8_LDB(B0, 0, 0); PG8_LDB(B1, 0, 1); PG8_SCHED; PG8_LDA(At, 0, 0); PG8_STAGE(PG8_SA(1, 1), a1 + hstepA, voffA);
;             PG8_WAIT_V(8); PG8_WAIT_L(0); PG8_BAR; PG8_MMA(0, 0, At, B0); PG8_MMA(0, 1, At, B1); PG8_BAR; PG8_SCHED;
;             PG8_LDA(At, 0, 1); PG8_STAGE(PG8_SB(0, 0), b2, voffB); PG8_STAGE(PG8_SB(0, 1), b2 + hstepB, voffB); PG8_STAGE(PG8_SA(0, 0), a2, voffA);
;             PG8_WAIT_V(8); PG8_WAIT_L(0); PG8_BAR; PG8_MMA(1, 0, At, B0); PG8_MMA(1, 1, At, B1); PG8_BAR; PG8_SCHED;
.LBB0_580:
	s_ashr_i32 s25, s24, 31
	s_lshl_b64 s[0:1], s[24:25], 20
	v_readlane_b32 s26, v255, 9
	v_readlane_b32 s27, v255, 10
	s_add_u32 s26, s26, s0
	s_addc_u32 s27, s27, s1
	s_and_b64 s[0:1], s[36:37], exec
	s_cselect_b32 s25, s27, s23
	s_cselect_b32 s50, s26, s22
	s_ashr_i32 s21, s20, 31
	s_lshl_b64 s[0:1], s[20:21], 20
	v_readlane_b32 s21, v253, 32
	s_add_u32 s28, s21, s0
	v_readlane_b32 s0, v253, 33
	s_addc_u32 s29, s0, s1
	s_and_b64 s[0:1], s[36:37], exec
	s_cselect_b32 s21, s29, s31
	s_cselect_b32 s51, s28, s30
	s_add_u32 s22, s22, 0x84000
	s_addc_u32 s23, s23, 0
	s_add_u32 s54, s30, 0x8000
	v_mov_b32_e32 v2, 0
	s_addc_u32 s55, s31, 0
	s_mov_b32 s56, -2
	v_readlane_b32 s0, v254, 19
	s_add_u32 s0, s22, 0xfff84000
	s_addc_u32 s1, s23, -1
	s_cmp_eq_u32 s56, 28
	s_cselect_b32 s34, s50, s0
	s_cselect_b32 s35, s25, s1
	s_cselect_b32 s38, s51, s54
	s_cselect_b32 s39, s21, s55
	s_add_u32 s30, s34, 0x4000
	s_addc_u32 s31, s35, 0
	s_add_i32 s0, 0, 0x10000
	v_add_u32_e32 v142, s0, v146
	s_add_i32 s33, 0, 0x14000
	ds_read_b128 v[132:135], v142
	ds_read_b128 v[136:139], v142 offset:1024
	ds_read_b128 v[148:151], v142 offset:2048
	ds_read_b128 v[152:155], v142 offset:3072
	v_add_u32_e32 v142, s33, v146
	ds_read_b128 v[156:159], v142
	ds_read_b128 v[160:163], v142 offset:1024
	ds_read_b128 v[164:167], v142 offset:2048
	ds_read_b128 v[168:171], v142 offset:3072
	v_lshl_add_u64 v[144:145], s[22:23], 0, v[130:131]
	s_add_i32 m0, s10, 0xc000
	ds_read_b128 v[172:175], v147
	ds_read_b128 v[176:179], v147 offset:1024
	ds_read_b128 v[180:183], v147 offset:2048
	ds_read_b128 v[184:187], v147 offset:3072
	ds_read_b128 v[188:191], v147 offset:4096
	ds_read_b128 v[194:197], v147 offset:5120
	ds_read_b128 v[206:209], v147 offset:6144
	ds_read_b128 v[210:213], v147 offset:7168
	global_load_lds_dwordx4 v[144:145], off
	v_lshl_add_u64 v[144:145], s[22:23], 0, v[140:141]
	s_add_i32 m0, s10, 0xe000
	s_nop 0
	global_load_lds_dwordx4 v[144:145], off
	s_waitcnt vmcnt(8)
	s_waitcnt lgkmcnt(0)
	s_barrier
	s_setprio 1
	s_waitcnt lgkmcnt(0)
	v_mfma_f32_16x16x32_bf16 v[126:129], v[132:135], v[172:175], 0
	v_mfma_f32_16x16x32_bf16 v[122:125], v[148:151], v[172:175], 0
	v_mfma_f32_16x16x32_bf16 v[118:121], v[132:135], v[180:183], 0
	v_mfma_f32_16x16x32_bf16 v[114:117], v[148:151], v[180:183], 0
	v_mfma_f32_16x16x32_bf16 v[110:113], v[132:135], v[188:191], 0
	v_mfma_f32_16x16x32_bf16 v[106:109], v[148:151], v[188:191], 0
	v_mfma_f32_16x16x32_bf16 v[102:105], v[132:135], v[206:209], 0
	v_mfma_f32_16x16x32_bf16 v[98:101], v[148:151], v[206:209], 0
	v_mfma_f32_16x16x32_bf16 v[126:129], v[136:139], v[176:179], v[126:129]
	v_mfma_f32_16x16x32_bf16 v[122:125], v[152:155], v[176:179], v[122:125]
	v_mfma_f32_16x16x32_bf16 v[118:121], v[136:139], v[184:187], v[118:121]
	v_mfma_f32_16x16x32_bf16 v[114:117], v[152:155], v[184:187], v[114:117]
	v_mfma_f32_16x16x32_bf16 v[110:113], v[136:139], v[194:197], v[110:113]
	v_mfma_f32_16x16x32_bf16 v[106:109], v[152:155], v[194:197], v[106:109]
	v_mfma_f32_16x16x32_bf16 v[102:105], v[136:139], v[210:213], v[102:105]
	v_mfma_f32_16x16x32_bf16 v[98:101], v[152:155], v[210:213], v[98:101]
	s_setprio 0
	s_setprio 1
	v_mfma_f32_16x16x32_bf16 v[62:65], v[156:159], v[172:175], 0
	v_mfma_f32_16x16x32_bf16 v[58:61], v[164:167], v[172:175], 0
	v_mfma_f32_16x16x32_bf16 v[54:57], v[156:159], v[180:183], 0
	v_mfma_f32_16x16x32_bf16 v[50:53], v[164:167], v[180:183], 0
	v_mfma_f32_16x16x32_bf16 v[46:49], v[156:159], v[188:191], 0
	v_mfma_f32_16x16x32_bf16 v[42:45], v[164:167], v[188:191], 0
	v_mfma_f32_16x16x32_bf16 v[38:41], v[156:159], v[206:209], 0
	v_mfma_f32_16x16x32_bf16 v[34:37], v[164:167], v[206:209], 0
	v_mfma_f32_16x16x32_bf16 v[62:65], v[160:163], v[176:179], v[62:65]
	v_mfma_f32_16x16x32_bf16 v[58:61], v[168:171], v[176:179], v[58:61]
	v_mfma_f32_16x16x32_bf16 v[54:57], v[160:163], v[184:187], v[54:57]
	v_mfma_f32_16x16x32_bf16 v[50:53], v[168:171], v[184:187], v[50:53]
	v_mfma_f32_16x16x32_bf16 v[46:49], v[160:163], v[194:197], v[46:49]
	v_mfma_f32_16x16x32_bf16 v[42:45], v[168:171], v[194:197], v[42:45]
	v_mfma_f32_16x16x32_bf16 v[38:41], v[160:163], v[210:213], v[38:41]
	s_barrier
	v_mfma_f32_16x16x32_bf16 v[34:37], v[168:171], v[210:213], v[34:37]
	s_setprio 0
	s_add_i32 s0, s0, s2
	v_lshl_add_u64 v[144:145], s[38:39], 0, v[130:131]
	s_mov_b32 m0, s0
	ds_read_b128 v[172:175], v147 offset:16384
	ds_read_b128 v[176:179], v147 offset:17408
	ds_read_b128 v[180:183], v147 offset:18432
	ds_read_b128 v[184:187], v147 offset:19456
	ds_read_b128 v[188:191], v147 offset:20480
	ds_read_b128 v[194:197], v147 offset:21504
	ds_read_b128 v[206:209], v147 offset:22528
	ds_read_b128 v[210:213], v147 offset:23552
	global_load_lds_dwordx4 v[144:145], off
	s_add_i32 m0, s0, 0x2000
	s_add_u32 s0, s38, 0x80000
	v_lshl_add_u64 v[144:145], s[38:39], 0, v[140:141]
	s_addc_u32 s1, s39, 0
	s_add_i32 s33, s33, s2
	global_load_lds_dwordx4 v[144:145], off
	v_lshl_add_u64 v[144:145], s[0:1], 0, v[130:131]
	s_mov_b32 m0, s33
	s_nop 0
	global_load_lds_dwordx4 v[144:145], off
	v_lshl_add_u64 v[144:145], s[0:1], 0, v[140:141]
	s_add_i32 m0, s33, 0x2000
	s_nop 0
	global_load_lds_dwordx4 v[144:145], off
	v_lshl_add_u64 v[144:145], s[34:35], 0, v[130:131]
	s_mov_b32 m0, s10
	s_nop 0
	global_load_lds_dwordx4 v[144:145], off
	v_lshl_add_u64 v[144:145], s[34:35], 0, v[140:141]
	s_mov_b32 m0, s40
	s_nop 0
	global_load_lds_dwordx4 v[144:145], off
	s_waitcnt vmcnt(8)
	s_waitcnt lgkmcnt(0)
	s_barrier
; #define PG8_STAGE(bufoff, gbase, voff) do { _Pragma("unroll") for (int _i = 0; _i < 2; ++_i) \
;         __builtin_amdgcn_global_load_lds((const unsigned*)((const char*)(gbase) + (voff)[_i]), (LAS unsigned*)(lds + (bufoff) + ldsw + _i * 8192), 16, 0, 0); } while (0)
; #define PG8_LDA(dst, b, h) do { _Pragma("unroll") for (int m = 0; m < 4; ++m) _Pragma("unroll") for (int k = 0; k < 2; ++k) dst[m][k] = *(const LAS bf16x8*)(lds + PG8_SA(b, h) + aoff + m * 2048 + k * 1024); } while (0)
; #define PG8_LDB(dst, b, h) do { _Pragma("unroll") for (int n = 0; n < 2; ++n) _Pragma("unroll") for (int k = 0; k < 2; ++k) dst[n][k] = *(const LAS bf16x8*)(lds + PG8_SB(b, h) + boff + n * 2048 + k * 1024); } while (0)
; #define PG8_MMA(ai, bj, At, Bt) do { __builtin_amdgcn_s_setprio(1); _Pragma("unroll") for (int m = 0; m < 4; ++m) _Pragma("unroll") for (int n = 0; n < 2; ++n) _Pragma("unroll") for (int k = 0; k < 2; ++k) \
;         acc[ai][bj][m][n] = __builtin_amdgcn_mfma_f32_16x16x32_bf16(Bt[n][k], At[m][k], acc[ai][bj][m][n], 0, 0, 0); __builtin_amdgcn_s_setprio(0); } while (0)
; #define PG8_WAIT_V(n) asm volatile("s_waitcnt vmcnt(" #n ")" ::: "memory")
; #define PG8_WAIT_L(n) asm volatile("s_waitcnt lgkmcnt(" #n ")" ::: "memory")
; #define PG8_BAR __builtin_amdgcn_s_barrier()
; #define PG8_SCHED __builtin_amdgcn_sched_barrier(0)
; template <class Epi, bool ALIGN_EPI = true, bool SP2 = true>
; __device__ __forceinline__ void gemm_phase(LAS unsigned char* lds, const Gemm g, const StaticOrder& S, const Epi& E, unsigned long long& tacc, const int tmode) {
;     ...
;             PG8_WAIT_V(8); PG8_WAIT_L(0); PG8_BAR; PG8_MMA(1, 0, At, B0); PG8_MMA(1, 1, At, B1); PG8_BAR; PG8_SCHED;
;             PG8_LDB(B0, 1, 0); PG8_LDB(B1, 1, 1); PG8_SCHED; PG8_LDA(At, 1, 0); PG8_STAGE(PG8_SA(0, 1), a2 + hstepA, voffA);
;             PG8_WAIT_V(8); PG8_WAIT_L(0); PG8_BAR; PG8_MMA(0, 0, At, B0); PG8_MMA(0, 1, At, B1); PG8_BAR; PG8_SCHED;
	s_setprio 1
	s_waitcnt lgkmcnt(0)
	v_mfma_f32_16x16x32_bf16 v[94:97], v[132:135], v[172:175], 0
	v_mfma_f32_16x16x32_bf16 v[90:93], v[148:151], v[172:175], 0
	v_mfma_f32_16x16x32_bf16 v[86:89], v[132:135], v[180:183], 0
	v_mfma_f32_16x16x32_bf16 v[82:85], v[148:151], v[180:183], 0
	v_mfma_f32_16x16x32_bf16 v[78:81], v[132:135], v[188:191], 0
	v_mfma_f32_16x16x32_bf16 v[74:77], v[148:151], v[188:191], 0
	v_mfma_f32_16x16x32_bf16 v[70:73], v[132:135], v[206:209], 0
	v_mfma_f32_16x16x32_bf16 v[66:69], v[148:151], v[206:209], 0
	v_mfma_f32_16x16x32_bf16 v[94:97], v[136:139], v[176:179], v[94:97]
	v_mfma_f32_16x16x32_bf16 v[90:93], v[152:155], v[176:179], v[90:93]
	v_mfma_f32_16x16x32_bf16 v[86:89], v[136:139], v[184:187], v[86:89]
	v_mfma_f32_16x16x32_bf16 v[82:85], v[152:155], v[184:187], v[82:85]
	v_mfma_f32_16x16x32_bf16 v[78:81], v[136:139], v[194:197], v[78:81]
	v_mfma_f32_16x16x32_bf16 v[74:77], v[152:155], v[194:197], v[74:77]
	v_mfma_f32_16x16x32_bf16 v[70:73], v[136:139], v[210:213], v[70:73]
	v_mfma_f32_16x16x32_bf16 v[66:69], v[152:155], v[210:213], v[66:69]
	s_setprio 0
	s_setprio 1
	v_mfma_f32_16x16x32_bf16 v[30:33], v[156:159], v[172:175], 0
	v_mfma_f32_16x16x32_bf16 v[26:29], v[164:167], v[172:175], 0
	v_mfma_f32_16x16x32_bf16 v[22:25], v[156:159], v[180:183], 0
	v_mfma_f32_16x16x32_bf16 v[18:21], v[164:167], v[180:183], 0
	v_mfma_f32_16x16x32_bf16 v[14:17], v[156:159], v[188:191], 0
	v_mfma_f32_16x16x32_bf16 v[10:13], v[164:167], v[188:191], 0
	v_mfma_f32_16x16x32_bf16 v[6:9], v[156:159], v[206:209], 0
	v_mfma_f32_16x16x32_bf16 v[2:5], v[164:167], v[206:209], 0
	v_mfma_f32_16x16x32_bf16 v[30:33], v[160:163], v[176:179], v[30:33]
	v_mfma_f32_16x16x32_bf16 v[26:29], v[168:171], v[176:179], v[26:29]
	v_mfma_f32_16x16x32_bf16 v[22:25], v[160:163], v[184:187], v[22:25]
	v_mfma_f32_16x16x32_bf16 v[18:21], v[168:171], v[184:187], v[18:21]
	v_mfma_f32_16x16x32_bf16 v[14:17], v[160:163], v[194:197], v[14:17]
	v_mfma_f32_16x16x32_bf16 v[10:13], v[168:171], v[194:197], v[10:13]
	v_mfma_f32_16x16x32_bf16 v[6:9], v[160:163], v[210:213], v[6:9]
	s_barrier
	v_mfma_f32_16x16x32_bf16 v[2:5], v[168:171], v[210:213], v[2:5]
	s_setprio 0
	s_add_i32 s33, 0, 0x18000
	v_add_u32_e32 v142, s33, v146
	s_add_i32 s57, 0, 0x1c000
	ds_read_b128 v[132:135], v142
	ds_read_b128 v[136:139], v142 offset:1024
	ds_read_b128 v[148:151], v142 offset:2048
	ds_read_b128 v[152:155], v142 offset:3072
	v_add_u32_e32 v142, s57, v146
	ds_read_b128 v[156:159], v142
	ds_read_b128 v[160:163], v142 offset:1024
	ds_read_b128 v[164:167], v142 offset:2048
	ds_read_b128 v[168:171], v142 offset:3072
	s_add_u32 s0, s34, 0x80000
	s_addc_u32 s1, s35, 0
	s_mov_b32 m0, s41
	v_lshl_add_u64 v[144:145], s[0:1], 0, v[130:131]
	ds_read_b128 v[172:175], v147 offset:32768
	ds_read_b128 v[176:179], v147 offset:33792
	ds_read_b128 v[180:183], v147 offset:34816
	ds_read_b128 v[184:187], v147 offset:35840
	ds_read_b128 v[188:191], v147 offset:36864
	ds_read_b128 v[194:197], v147 offset:37888
	ds_read_b128 v[206:209], v147 offset:38912
	ds_read_b128 v[210:213], v147 offset:39936
	global_load_lds_dwordx4 v[144:145], off
	v_lshl_add_u64 v[144:145], s[0:1], 0, v[140:141]
	s_mov_b32 m0, s42
	s_nop 0
	global_load_lds_dwordx4 v[144:145], off
	s_waitcnt vmcnt(8)
	s_waitcnt lgkmcnt(0)
	s_barrier
	s_setprio 1
	s_waitcnt lgkmcnt(0)
	v_mfma_f32_16x16x32_bf16 v[126:129], v[132:135], v[172:175], v[126:129]
	v_mfma_f32_16x16x32_bf16 v[122:125], v[148:151], v[172:175], v[122:125]
	v_mfma_f32_16x16x32_bf16 v[118:121], v[132:135], v[180:183], v[118:121]
	v_mfma_f32_16x16x32_bf16 v[114:117], v[148:151], v[180:183], v[114:117]
	v_mfma_f32_16x16x32_bf16 v[110:113], v[132:135], v[188:191], v[110:113]
	v_mfma_f32_16x16x32_bf16 v[106:109], v[148:151], v[188:191], v[106:109]
	v_mfma_f32_16x16x32_bf16 v[102:105], v[132:135], v[206:209], v[102:105]
	v_mfma_f32_16x16x32_bf16 v[98:101], v[148:151], v[206:209], v[98:101]
	v_mfma_f32_16x16x32_bf16 v[126:129], v[136:139], v[176:179], v[126:129]
	v_mfma_f32_16x16x32_bf16 v[122:125], v[152:155], v[176:179], v[122:125]
	v_mfma_f32_16x16x32_bf16 v[118:121], v[136:139], v[184:187], v[118:121]
	v_mfma_f32_16x16x32_bf16 v[114:117], v[152:155], v[184:187], v[114:117]
	v_mfma_f32_16x16x32_bf16 v[110:113], v[136:139], v[194:197], v[110:113]
	v_mfma_f32_16x16x32_bf16 v[106:109], v[152:155], v[194:197], v[106:109]
	v_mfma_f32_16x16x32_bf16 v[102:105], v[136:139], v[210:213], v[102:105]
	v_mfma_f32_16x16x32_bf16 v[98:101], v[152:155], v[210:213], v[98:101]
	s_setprio 0
	s_setprio 1
	v_mfma_f32_16x16x32_bf16 v[62:65], v[156:159], v[172:175], v[62:65]
	v_mfma_f32_16x16x32_bf16 v[58:61], v[164:167], v[172:175], v[58:61]
	v_mfma_f32_16x16x32_bf16 v[54:57], v[156:159], v[180:183], v[54:57]
	v_mfma_f32_16x16x32_bf16 v[50:53], v[164:167], v[180:183], v[50:53]
	v_mfma_f32_16x16x32_bf16 v[46:49], v[156:159], v[188:191], v[46:49]
	v_mfma_f32_16x16x32_bf16 v[42:45], v[164:167], v[188:191], v[42:45]
	v_mfma_f32_16x16x32_bf16 v[38:41], v[156:159], v[206:209], v[38:41]
	v_mfma_f32_16x16x32_bf16 v[34:37], v[164:167], v[206:209], v[34:37]
	v_mfma_f32_16x16x32_bf16 v[62:65], v[160:163], v[176:179], v[62:65]
	v_mfma_f32_16x16x32_bf16 v[58:61], v[168:171], v[176:179], v[58:61]
	v_mfma_f32_16x16x32_bf16 v[54:57], v[160:163], v[184:187], v[54:57]
	v_mfma_f32_16x16x32_bf16 v[50:53], v[168:171], v[184:187], v[50:53]
	v_mfma_f32_16x16x32_bf16 v[46:49], v[160:163], v[194:197], v[46:49]
	v_mfma_f32_16x16x32_bf16 v[42:45], v[168:171], v[194:197], v[42:45]
	v_mfma_f32_16x16x32_bf16 v[38:41], v[160:163], v[210:213], v[38:41]
	s_barrier
; #define PG8_STAGE(bufoff, gbase, voff) do { _Pragma("unroll") for (int _i = 0; _i < 2; ++_i) \
;         __builtin_amdgcn_global_load_lds((const unsigned*)((const char*)(gbase) + (voff)[_i]), (LAS unsigned*)(lds + (bufoff) + ldsw + _i * 8192), 16, 0, 0); } while (0)
; #define PG8_LDA(dst, b, h) do { _Pragma("unroll") for (int m = 0; m < 4; ++m) _Pragma("unroll") for (int k = 0; k < 2; ++k) dst[m][k] = *(const LAS bf16x8*)(lds + PG8_SA(b, h) + aoff + m * 2048 + k * 1024); } while (0)
; #define PG8_MMA(ai, bj, At, Bt) do { __builtin_amdgcn_s_setprio(1); _Pragma("unroll") for (int m = 0; m < 4; ++m) _Pragma("unroll") for (int n = 0; n < 2; ++n) _Pragma("unroll") for (int k = 0; k < 2; ++k) \
;         acc[ai][bj][m][n] = __builtin_amdgcn_mfma_f32_16x16x32_bf16(Bt[n][k], At[m][k], acc[ai][bj][m][n], 0, 0, 0); __builtin_amdgcn_s_setprio(0); } while (0)
; #define PG8_WAIT_V(n) asm volatile("s_waitcnt vmcnt(" #n ")" ::: "memory")
; #define PG8_WAIT_L(n) asm volatile("s_waitcnt lgkmcnt(" #n ")" ::: "memory")
; #define PG8_BAR __builtin_amdgcn_s_barrier()
; #define PG8_SCHED __builtin_amdgcn_sched_barrier(0)
; template <class Epi, bool ALIGN_EPI = true, bool SP2 = true>
; __device__ __forceinline__ void gemm_phase(LAS unsigned char* lds, const Gemm g, const StaticOrder& S, const Epi& E, unsigned long long& tacc, const int tmode) {
;     ...
;         for (int t = 0; t < nt; t += 2) {
;             const bool last = (t == nt - 2);
;             const char* a1 = cA + (size_t)(t + 1) * kstepA;
;             const char* a2 = last ? nA : cA + (size_t)(t + 2) * kstepA; const char* b2 = last ? nB : cB + (size_t)(t + 2) * kstepB;
;             const char* a3 = a2 + kstepA; const char* b3 = b2 + kstepB;
;     ...
;             PG8_LDA(At, 1, 1); PG8_STAGE(PG8_SB(1, 0), b3, voffB); PG8_STAGE(PG8_SB(1, 1), b3 + hstepB, voffB); PG8_STAGE(PG8_SA(1, 0), a3, voffA);
;             PG8_WAIT_V(8); PG8_WAIT_L(0); PG8_BAR; PG8_MMA(1, 0, At, B0); PG8_MMA(1, 1, At, B1); PG8_BAR; PG8_SCHED;
	v_mfma_f32_16x16x32_bf16 v[34:37], v[168:171], v[210:213], v[34:37]
	s_setprio 0
	s_add_u32 s0, s38, 0x4000
	s_addc_u32 s1, s39, 0
	s_add_i32 s33, s33, s2
	v_lshl_add_u64 v[144:145], s[0:1], 0, v[130:131]
	s_mov_b32 m0, s33
	ds_read_b128 v[172:175], v147 offset:49152
	ds_read_b128 v[176:179], v147 offset:50176
	ds_read_b128 v[180:183], v147 offset:51200
	ds_read_b128 v[184:187], v147 offset:52224
	ds_read_b128 v[188:191], v147 offset:53248
	ds_read_b128 v[194:197], v147 offset:54272
	ds_read_b128 v[206:209], v147 offset:55296
	ds_read_b128 v[210:213], v147 offset:56320
	global_load_lds_dwordx4 v[144:145], off
	s_add_i32 m0, s33, 0x2000
	v_lshl_add_u64 v[144:145], s[0:1], 0, v[140:141]
	s_add_u32 s0, s38, 0x84000
	s_addc_u32 s1, s39, 0
	s_add_i32 s33, s57, s2
	global_load_lds_dwordx4 v[144:145], off
	v_lshl_add_u64 v[144:145], s[0:1], 0, v[130:131]
	s_mov_b32 m0, s33
	s_nop 0
	global_load_lds_dwordx4 v[144:145], off
	v_lshl_add_u64 v[144:145], s[0:1], 0, v[140:141]
	s_add_i32 m0, s33, 0x2000
	s_nop 0
	global_load_lds_dwordx4 v[144:145], off
	v_lshl_add_u64 v[144:145], s[30:31], 0, v[130:131]
	s_mov_b32 m0, s45
	s_nop 0
	global_load_lds_dwordx4 v[144:145], off
	v_lshl_add_u64 v[144:145], s[30:31], 0, v[140:141]
	s_mov_b32 m0, s46
	s_nop 0
	global_load_lds_dwordx4 v[144:145], off
	s_waitcnt vmcnt(8)
	s_waitcnt lgkmcnt(0)
	s_barrier
	s_setprio 1
	s_waitcnt lgkmcnt(0)
	v_mfma_f32_16x16x32_bf16 v[94:97], v[132:135], v[172:175], v[94:97]
	v_mfma_f32_16x16x32_bf16 v[90:93], v[148:151], v[172:175], v[90:93]
	v_mfma_f32_16x16x32_bf16 v[86:89], v[132:135], v[180:183], v[86:89]
	v_mfma_f32_16x16x32_bf16 v[82:85], v[148:151], v[180:183], v[82:85]
	v_mfma_f32_16x16x32_bf16 v[78:81], v[132:135], v[188:191], v[78:81]
	v_mfma_f32_16x16x32_bf16 v[74:77], v[148:151], v[188:191], v[74:77]
	v_mfma_f32_16x16x32_bf16 v[70:73], v[132:135], v[206:209], v[70:73]
	v_mfma_f32_16x16x32_bf16 v[66:69], v[148:151], v[206:209], v[66:69]
	v_mfma_f32_16x16x32_bf16 v[94:97], v[136:139], v[176:179], v[94:97]
	v_mfma_f32_16x16x32_bf16 v[90:93], v[152:155], v[176:179], v[90:93]
	v_mfma_f32_16x16x32_bf16 v[86:89], v[136:139], v[184:187], v[86:89]
	v_mfma_f32_16x16x32_bf16 v[82:85], v[152:155], v[184:187], v[82:85]
	v_mfma_f32_16x16x32_bf16 v[78:81], v[136:139], v[194:197], v[78:81]
	v_mfma_f32_16x16x32_bf16 v[74:77], v[152:155], v[194:197], v[74:77]
	v_mfma_f32_16x16x32_bf16 v[70:73], v[136:139], v[210:213], v[70:73]
	v_mfma_f32_16x16x32_bf16 v[66:69], v[152:155], v[210:213], v[66:69]
	s_setprio 0
	s_setprio 1
	v_mfma_f32_16x16x32_bf16 v[30:33], v[156:159], v[172:175], v[30:33]
	v_mfma_f32_16x16x32_bf16 v[26:29], v[164:167], v[172:175], v[26:29]
	v_mfma_f32_16x16x32_bf16 v[22:25], v[156:159], v[180:183], v[22:25]
	v_mfma_f32_16x16x32_bf16 v[18:21], v[164:167], v[180:183], v[18:21]
	v_mfma_f32_16x16x32_bf16 v[14:17], v[156:159], v[188:191], v[14:17]
	v_mfma_f32_16x16x32_bf16 v[10:13], v[164:167], v[188:191], v[10:13]
	v_mfma_f32_16x16x32_bf16 v[6:9], v[156:159], v[206:209], v[6:9]
	v_mfma_f32_16x16x32_bf16 v[2:5], v[164:167], v[206:209], v[2:5]
	v_mfma_f32_16x16x32_bf16 v[30:33], v[160:163], v[176:179], v[30:33]
	v_mfma_f32_16x16x32_bf16 v[26:29], v[168:171], v[176:179], v[26:29]
	v_mfma_f32_16x16x32_bf16 v[22:25], v[160:163], v[184:187], v[22:25]
	v_mfma_f32_16x16x32_bf16 v[18:21], v[168:171], v[184:187], v[18:21]
	v_mfma_f32_16x16x32_bf16 v[14:17], v[160:163], v[194:197], v[14:17]
	v_mfma_f32_16x16x32_bf16 v[10:13], v[168:171], v[194:197], v[10:13]
	v_mfma_f32_16x16x32_bf16 v[6:9], v[160:163], v[210:213], v[6:9]
	s_barrier
	v_mfma_f32_16x16x32_bf16 v[2:5], v[168:171], v[210:213], v[2:5]
	s_setprio 0
	s_add_i32 s56, s56, 2
	s_add_u32 s22, s22, 0x8000
	s_addc_u32 s23, s23, 0
	s_add_u32 s54, s54, 0x8000
	s_addc_u32 s55, s55, 0
	s_cmp_lt_u32 s56, 30

; __device__ __forceinline__ const char* b_base(const Gemm& g, const Unit& u) { return (const char*)g.Bt + (size_t)u.pn * 2 * (g.K >> 6) * BLK; }
; #define PG8_STAGE(bufoff, gbase, voff) do { _Pragma("unroll") for (int _i = 0; _i < 2; ++_i) \
;         __builtin_amdgcn_global_load_lds((const unsigned*)((const char*)(gbase) + (voff)[_i]), (LAS unsigned*)(lds + (bufoff) + ldsw + _i * 8192), 16, 0, 0); } while (0)
; #define PG8_LDA(dst, b, h) do { _Pragma("unroll") for (int m = 0; m < 4; ++m) _Pragma("unroll") for (int k = 0; k < 2; ++k) dst[m][k] = *(const LAS bf16x8*)(lds + PG8_SA(b, h) + aoff + m * 2048 + k * 1024); } while (0)
; #define PG8_LDB(dst, b, h) do { _Pragma("unroll") for (int n = 0; n < 2; ++n) _Pragma("unroll") for (int k = 0; k < 2; ++k) dst[n][k] = *(const LAS bf16x8*)(lds + PG8_SB(b, h) + boff + n * 2048 + k * 1024); } while (0)
; #define PG8_BAR __builtin_amdgcn_s_barrier()
; template <class Epi, bool ALIGN_EPI = true, bool SP2 = true>
; __device__ __forceinline__ void gemm_phase(LAS unsigned char* lds, const Gemm g, const StaticOrder& S, const Epi& E, unsigned long long& tacc, const int tmode) {
;     ...
;         const bool has_next = S.next(ui + 1, nxt);
;         const char* nA = has_next ? a_base(g, nxt) : cA; const char* nB = has_next ? b_base(g, nxt) : cB;
;         unsigned long long tk0 = 0ull; if (tmode == 1) tk0 = __builtin_amdgcn_s_memrealtime(); if (tmode == 3) tk0 = (unsigned long long)clock64();
; #pragma unroll 1
;         for (int t = 0; t < nt; t += 2) {
;             const bool last = (t == nt - 2);
;             const char* a1 = cA + (size_t)(t + 1) * kstepA;
;             const char* a2 = last ? nA : cA + (size_t)(t + 2) * kstepA; const char* b2 = last ? nB : cB + (size_t)(t + 2) * kstepB;
;             const char* a3 = a2 + kstepA; const char* b3 = b2 + kstepB;
;             if constexpr (SP2) {
;             PG8_LDB(B0, 0, 0); PG8_LDB(B1, 0, 1); PG8_SCHED; PG8_LDA(At, 0, 0); PG8_STAGE(PG8_SA(1, 1), a1 + hstepA, voffA);
;             PG8_WAIT_V(8); PG8_WAIT_L(0); PG8_BAR; PG8_MMA(0, 0, At, B0); PG8_MMA(0, 1, At, B1); PG8_BAR; PG8_SCHED;
;             PG8_LDA(At, 0, 1); PG8_STAGE(PG8_SB(0, 0), b2, voffB); PG8_STAGE(PG8_SB(0, 1), b2 + hstepB, voffB); PG8_STAGE(PG8_SA(0, 0), a2, voffA);
;             PG8_WAIT_V(8); PG8_WAIT_L(0); PG8_BAR; PG8_MMA(1, 0, At, B0); PG8_MMA(1, 1, At, B1); PG8_BAR; PG8_SCHED;
.LBB0_738:
	s_ashr_i32 s25, s24, 31
	s_lshl_b64 s[0:1], s[24:25], 20
	v_readlane_b32 s26, v255, 9
	v_readlane_b32 s27, v255, 10
	s_add_u32 s26, s26, s0
	s_addc_u32 s27, s27, s1
	s_and_b64 s[0:1], s[38:39], exec
	s_cselect_b32 s25, s27, s23
	s_cselect_b32 s56, s26, s22
	s_ashr_i32 s21, s20, 31
	s_lshl_b64 s[0:1], s[20:21], 20
	s_add_u32 s28, s2, s0
	s_addc_u32 s29, s10, s1
	s_and_b64 s[0:1], s[38:39], exec
	s_cselect_b32 s21, s29, s31
	s_cselect_b32 s57, s28, s30
	s_add_u32 s22, s22, 0x84000
	s_addc_u32 s23, s23, 0
	s_add_u32 s60, s30, 0x8000
	v_mov_b32_e32 v2, 0
	s_addc_u32 s61, s31, 0
	s_mov_b32 s65, -2
	s_add_u32 s0, s22, 0xfff84000
	s_addc_u32 s1, s23, -1
	s_cmp_eq_u32 s65, 28
	s_cselect_b32 s34, s56, s0
	s_cselect_b32 s35, s25, s1
	s_cselect_b32 s40, s57, s60
	s_cselect_b32 s41, s21, s61
	s_add_u32 s30, s34, 0x4000
	s_addc_u32 s31, s35, 0
	s_add_i32 s0, 0, 0x10000
	v_add_u32_e32 v138, s0, v141
	s_add_i32 s33, 0, 0x14000
	ds_read_b128 v[134:137], v138
	ds_read_b128 v[144:147], v138 offset:1024
	ds_read_b128 v[148:151], v138 offset:2048
	ds_read_b128 v[152:155], v138 offset:3072
	v_add_u32_e32 v138, s33, v141
	ds_read_b128 v[156:159], v138
	ds_read_b128 v[160:163], v138 offset:1024
	ds_read_b128 v[164:167], v138 offset:2048
	ds_read_b128 v[168:171], v138 offset:3072
	v_lshl_add_u64 v[138:139], s[22:23], 0, v[130:131]
	s_add_i32 m0, s43, 0xc000
	ds_read_b128 v[172:175], v142
	ds_read_b128 v[176:179], v142 offset:1024
	ds_read_b128 v[180:183], v142 offset:2048
	ds_read_b128 v[184:187], v142 offset:3072
	ds_read_b128 v[188:191], v142 offset:4096
	ds_read_b128 v[206:209], v142 offset:5120
	ds_read_b128 v[210:213], v142 offset:6144
	ds_read_b128 v[214:217], v142 offset:7168
	global_load_lds_dwordx4 v[138:139], off
	v_lshl_add_u64 v[138:139], s[22:23], 0, v[132:133]
	s_add_i32 m0, s43, 0xe000
	s_nop 0
	global_load_lds_dwordx4 v[138:139], off
	s_waitcnt vmcnt(8)
	s_waitcnt lgkmcnt(0)
	s_barrier
	s_setprio 1
	s_waitcnt lgkmcnt(0)
	v_mfma_f32_16x16x32_bf16 v[126:129], v[134:137], v[172:175], 0
	v_mfma_f32_16x16x32_bf16 v[122:125], v[148:151], v[172:175], 0
	v_mfma_f32_16x16x32_bf16 v[110:113], v[134:137], v[180:183], 0
	v_mfma_f32_16x16x32_bf16 v[106:109], v[148:151], v[180:183], 0
	v_mfma_f32_16x16x32_bf16 v[94:97], v[134:137], v[188:191], 0
	v_mfma_f32_16x16x32_bf16 v[90:93], v[148:151], v[188:191], 0
	v_mfma_f32_16x16x32_bf16 v[78:81], v[134:137], v[210:213], 0
	v_mfma_f32_16x16x32_bf16 v[74:77], v[148:151], v[210:213], 0
	v_mfma_f32_16x16x32_bf16 v[126:129], v[144:147], v[176:179], v[126:129]
	v_mfma_f32_16x16x32_bf16 v[122:125], v[152:155], v[176:179], v[122:125]
	v_mfma_f32_16x16x32_bf16 v[110:113], v[144:147], v[184:187], v[110:113]
	v_mfma_f32_16x16x32_bf16 v[106:109], v[152:155], v[184:187], v[106:109]
	v_mfma_f32_16x16x32_bf16 v[94:97], v[144:147], v[206:209], v[94:97]
	v_mfma_f32_16x16x32_bf16 v[90:93], v[152:155], v[206:209], v[90:93]
	v_mfma_f32_16x16x32_bf16 v[78:81], v[144:147], v[214:217], v[78:81]
	v_mfma_f32_16x16x32_bf16 v[74:77], v[152:155], v[214:217], v[74:77]
	s_setprio 0
	s_setprio 1
	v_mfma_f32_16x16x32_bf16 v[118:121], v[156:159], v[172:175], 0
	v_mfma_f32_16x16x32_bf16 v[114:117], v[164:167], v[172:175], 0
	v_mfma_f32_16x16x32_bf16 v[102:105], v[156:159], v[180:183], 0
	v_mfma_f32_16x16x32_bf16 v[98:101], v[164:167], v[180:183], 0
	v_mfma_f32_16x16x32_bf16 v[86:89], v[156:159], v[188:191], 0
	v_mfma_f32_16x16x32_bf16 v[82:85], v[164:167], v[188:191], 0
	v_mfma_f32_16x16x32_bf16 v[70:73], v[156:159], v[210:213], 0
	v_mfma_f32_16x16x32_bf16 v[66:69], v[164:167], v[210:213], 0
	v_mfma_f32_16x16x32_bf16 v[118:121], v[160:163], v[176:179], v[118:121]
	v_mfma_f32_16x16x32_bf16 v[114:117], v[168:171], v[176:179], v[114:117]
	v_mfma_f32_16x16x32_bf16 v[102:105], v[160:163], v[184:187], v[102:105]
	v_mfma_f32_16x16x32_bf16 v[98:101], v[168:171], v[184:187], v[98:101]
	v_mfma_f32_16x16x32_bf16 v[86:89], v[160:163], v[206:209], v[86:89]
	v_mfma_f32_16x16x32_bf16 v[82:85], v[168:171], v[206:209], v[82:85]
	v_mfma_f32_16x16x32_bf16 v[70:73], v[160:163], v[214:217], v[70:73]
	s_barrier
	v_mfma_f32_16x16x32_bf16 v[66:69], v[168:171], v[214:217], v[66:69]
	s_setprio 0
	s_add_i32 s0, s0, s42
	v_lshl_add_u64 v[138:139], s[40:41], 0, v[130:131]
	s_mov_b32 m0, s0
	ds_read_b128 v[172:175], v142 offset:16384
	ds_read_b128 v[176:179], v142 offset:17408
	ds_read_b128 v[180:183], v142 offset:18432
	ds_read_b128 v[184:187], v142 offset:19456
	ds_read_b128 v[188:191], v142 offset:20480
	ds_read_b128 v[206:209], v142 offset:21504
	ds_read_b128 v[210:213], v142 offset:22528
	ds_read_b128 v[214:217], v142 offset:23552
	global_load_lds_dwordx4 v[138:139], off
	s_add_i32 m0, s0, 0x2000
	s_add_u32 s0, s40, 0x80000
	v_lshl_add_u64 v[138:139], s[40:41], 0, v[132:133]
	s_addc_u32 s1, s41, 0
	s_add_i32 s33, s33, s42
	global_load_lds_dwordx4 v[138:139], off
	v_lshl_add_u64 v[138:139], s[0:1], 0, v[130:131]
	s_mov_b32 m0, s33
	s_nop 0
	global_load_lds_dwordx4 v[138:139], off
	v_lshl_add_u64 v[138:139], s[0:1], 0, v[132:133]
	s_add_i32 m0, s33, 0x2000
	s_nop 0
	global_load_lds_dwordx4 v[138:139], off
	v_lshl_add_u64 v[138:139], s[34:35], 0, v[130:131]
	s_mov_b32 m0, s43
	s_nop 0
	global_load_lds_dwordx4 v[138:139], off
	v_lshl_add_u64 v[138:139], s[34:35], 0, v[132:133]
	s_mov_b32 m0, s44
	s_nop 0
	global_load_lds_dwordx4 v[138:139], off
	s_waitcnt vmcnt(8)
	s_waitcnt lgkmcnt(0)
	s_barrier
; #define PG8_STAGE(bufoff, gbase, voff) do { _Pragma("unroll") for (int _i = 0; _i < 2; ++_i) \
;         __builtin_amdgcn_global_load_lds((const unsigned*)((const char*)(gbase) + (voff)[_i]), (LAS unsigned*)(lds + (bufoff) + ldsw + _i * 8192), 16, 0, 0); } while (0)
; #define PG8_LDA(dst, b, h) do { _Pragma("unroll") for (int m = 0; m < 4; ++m) _Pragma("unroll") for (int k = 0; k < 2; ++k) dst[m][k] = *(const LAS bf16x8*)(lds + PG8_SA(b, h) + aoff + m * 2048 + k * 1024); } while (0)
; #define PG8_LDB(dst, b, h) do { _Pragma("unroll") for (int n = 0; n < 2; ++n) _Pragma("unroll") for (int k = 0; k < 2; ++k) dst[n][k] = *(const LAS bf16x8*)(lds + PG8_SB(b, h) + boff + n * 2048 + k * 1024); } while (0)
; #define PG8_MMA(ai, bj, At, Bt) do { __builtin_amdgcn_s_setprio(1); _Pragma("unroll") for (int m = 0; m < 4; ++m) _Pragma("unroll") for (int n = 0; n < 2; ++n) _Pragma("unroll") for (int k = 0; k < 2; ++k) \
;         acc[ai][bj][m][n] = __builtin_amdgcn_mfma_f32_16x16x32_bf16(Bt[n][k], At[m][k], acc[ai][bj][m][n], 0, 0, 0); __builtin_amdgcn_s_setprio(0); } while (0)
; #define PG8_WAIT_V(n) asm volatile("s_waitcnt vmcnt(" #n ")" ::: "memory")
; #define PG8_WAIT_L(n) asm volatile("s_waitcnt lgkmcnt(" #n ")" ::: "memory")
; #define PG8_BAR __builtin_amdgcn_s_barrier()
; #define PG8_SCHED __builtin_amdgcn_sched_barrier(0)
; template <class Epi, bool ALIGN_EPI = true, bool SP2 = true>
; __device__ __forceinline__ void gemm_phase(LAS unsigned char* lds, const Gemm g, const StaticOrder& S, const Epi& E, unsigned long long& tacc, const int tmode) {
;     ...
;             PG8_WAIT_V(8); PG8_WAIT_L(0); PG8_BAR; PG8_MMA(1, 0, At, B0); PG8_MMA(1, 1, At, B1); PG8_BAR; PG8_SCHED;
;             PG8_LDB(B0, 1, 0); PG8_LDB(B1, 1, 1); PG8_SCHED; PG8_LDA(At, 1, 0); PG8_STAGE(PG8_SA(0, 1), a2 + hstepA, voffA);
;             PG8_WAIT_V(8); PG8_WAIT_L(0); PG8_BAR; PG8_MMA(0, 0, At, B0); PG8_MMA(0, 1, At, B1); PG8_BAR; PG8_SCHED;
	s_setprio 1
	s_waitcnt lgkmcnt(0)
	v_mfma_f32_16x16x32_bf16 v[62:65], v[134:137], v[172:175], 0
	v_mfma_f32_16x16x32_bf16 v[58:61], v[148:151], v[172:175], 0
	v_mfma_f32_16x16x32_bf16 v[46:49], v[134:137], v[180:183], 0
	v_mfma_f32_16x16x32_bf16 v[42:45], v[148:151], v[180:183], 0
	v_mfma_f32_16x16x32_bf16 v[30:33], v[134:137], v[188:191], 0
	v_mfma_f32_16x16x32_bf16 v[26:29], v[148:151], v[188:191], 0
	v_mfma_f32_16x16x32_bf16 v[14:17], v[134:137], v[210:213], 0
	v_mfma_f32_16x16x32_bf16 v[10:13], v[148:151], v[210:213], 0
	v_mfma_f32_16x16x32_bf16 v[62:65], v[144:147], v[176:179], v[62:65]
	v_mfma_f32_16x16x32_bf16 v[58:61], v[152:155], v[176:179], v[58:61]
	v_mfma_f32_16x16x32_bf16 v[46:49], v[144:147], v[184:187], v[46:49]
	v_mfma_f32_16x16x32_bf16 v[42:45], v[152:155], v[184:187], v[42:45]
	v_mfma_f32_16x16x32_bf16 v[30:33], v[144:147], v[206:209], v[30:33]
	v_mfma_f32_16x16x32_bf16 v[26:29], v[152:155], v[206:209], v[26:29]
	v_mfma_f32_16x16x32_bf16 v[14:17], v[144:147], v[214:217], v[14:17]
	v_mfma_f32_16x16x32_bf16 v[10:13], v[152:155], v[214:217], v[10:13]
	s_setprio 0
	s_setprio 1
	v_mfma_f32_16x16x32_bf16 v[54:57], v[156:159], v[172:175], 0
	v_mfma_f32_16x16x32_bf16 v[50:53], v[164:167], v[172:175], 0
	v_mfma_f32_16x16x32_bf16 v[38:41], v[156:159], v[180:183], 0
	v_mfma_f32_16x16x32_bf16 v[34:37], v[164:167], v[180:183], 0
	v_mfma_f32_16x16x32_bf16 v[22:25], v[156:159], v[188:191], 0
	v_mfma_f32_16x16x32_bf16 v[18:21], v[164:167], v[188:191], 0
	v_mfma_f32_16x16x32_bf16 v[6:9], v[156:159], v[210:213], 0
	v_mfma_f32_16x16x32_bf16 v[2:5], v[164:167], v[210:213], 0
	v_mfma_f32_16x16x32_bf16 v[54:57], v[160:163], v[176:179], v[54:57]
	v_mfma_f32_16x16x32_bf16 v[50:53], v[168:171], v[176:179], v[50:53]
	v_mfma_f32_16x16x32_bf16 v[38:41], v[160:163], v[184:187], v[38:41]
	v_mfma_f32_16x16x32_bf16 v[34:37], v[168:171], v[184:187], v[34:37]
	v_mfma_f32_16x16x32_bf16 v[22:25], v[160:163], v[206:209], v[22:25]
	v_mfma_f32_16x16x32_bf16 v[18:21], v[168:171], v[206:209], v[18:21]
	v_mfma_f32_16x16x32_bf16 v[6:9], v[160:163], v[214:217], v[6:9]
	s_barrier
	v_mfma_f32_16x16x32_bf16 v[2:5], v[168:171], v[214:217], v[2:5]
	s_setprio 0
	s_add_i32 s33, 0, 0x18000
	v_add_u32_e32 v138, s33, v141
	s_add_i32 s64, 0, 0x1c000
	ds_read_b128 v[134:137], v138
	ds_read_b128 v[144:147], v138 offset:1024
	ds_read_b128 v[148:151], v138 offset:2048
	ds_read_b128 v[152:155], v138 offset:3072
	v_add_u32_e32 v138, s64, v141
	ds_read_b128 v[156:159], v138
	ds_read_b128 v[160:163], v138 offset:1024
	ds_read_b128 v[164:167], v138 offset:2048
	ds_read_b128 v[168:171], v138 offset:3072
	s_add_u32 s0, s34, 0x80000
	s_addc_u32 s1, s35, 0
	s_mov_b32 m0, s45
	v_lshl_add_u64 v[138:139], s[0:1], 0, v[130:131]
	ds_read_b128 v[172:175], v142 offset:32768
	ds_read_b128 v[176:179], v142 offset:33792
	ds_read_b128 v[180:183], v142 offset:34816
	ds_read_b128 v[184:187], v142 offset:35840
	ds_read_b128 v[188:191], v142 offset:36864
	ds_read_b128 v[206:209], v142 offset:37888
	ds_read_b128 v[210:213], v142 offset:38912
	ds_read_b128 v[214:217], v142 offset:39936
	global_load_lds_dwordx4 v[138:139], off
	v_lshl_add_u64 v[138:139], s[0:1], 0, v[132:133]
	s_mov_b32 m0, s46
	s_nop 0
	global_load_lds_dwordx4 v[138:139], off
	s_waitcnt vmcnt(8)
	s_waitcnt lgkmcnt(0)
	s_barrier
	s_setprio 1
	s_waitcnt lgkmcnt(0)
	v_mfma_f32_16x16x32_bf16 v[126:129], v[134:137], v[172:175], v[126:129]
	v_mfma_f32_16x16x32_bf16 v[122:125], v[148:151], v[172:175], v[122:125]
	v_mfma_f32_16x16x32_bf16 v[110:113], v[134:137], v[180:183], v[110:113]
	v_mfma_f32_16x16x32_bf16 v[106:109], v[148:151], v[180:183], v[106:109]
	v_mfma_f32_16x16x32_bf16 v[94:97], v[134:137], v[188:191], v[94:97]
	v_mfma_f32_16x16x32_bf16 v[90:93], v[148:151], v[188:191], v[90:93]
	v_mfma_f32_16x16x32_bf16 v[78:81], v[134:137], v[210:213], v[78:81]
	v_mfma_f32_16x16x32_bf16 v[74:77], v[148:151], v[210:213], v[74:77]
	v_mfma_f32_16x16x32_bf16 v[126:129], v[144:147], v[176:179], v[126:129]
	v_mfma_f32_16x16x32_bf16 v[122:125], v[152:155], v[176:179], v[122:125]
	v_mfma_f32_16x16x32_bf16 v[110:113], v[144:147], v[184:187], v[110:113]
	v_mfma_f32_16x16x32_bf16 v[106:109], v[152:155], v[184:187], v[106:109]
	v_mfma_f32_16x16x32_bf16 v[94:97], v[144:147], v[206:209], v[94:97]
	v_mfma_f32_16x16x32_bf16 v[90:93], v[152:155], v[206:209], v[90:93]
	v_mfma_f32_16x16x32_bf16 v[78:81], v[144:147], v[214:217], v[78:81]
	v_mfma_f32_16x16x32_bf16 v[74:77], v[152:155], v[214:217], v[74:77]
	s_setprio 0
	s_setprio 1
	v_mfma_f32_16x16x32_bf16 v[118:121], v[156:159], v[172:175], v[118:121]
	v_mfma_f32_16x16x32_bf16 v[114:117], v[164:167], v[172:175], v[114:117]
	v_mfma_f32_16x16x32_bf16 v[102:105], v[156:159], v[180:183], v[102:105]
	v_mfma_f32_16x16x32_bf16 v[98:101], v[164:167], v[180:183], v[98:101]
	v_mfma_f32_16x16x32_bf16 v[86:89], v[156:159], v[188:191], v[86:89]
	v_mfma_f32_16x16x32_bf16 v[82:85], v[164:167], v[188:191], v[82:85]
	v_mfma_f32_16x16x32_bf16 v[70:73], v[156:159], v[210:213], v[70:73]
	v_mfma_f32_16x16x32_bf16 v[66:69], v[164:167], v[210:213], v[66:69]
	v_mfma_f32_16x16x32_bf16 v[118:121], v[160:163], v[176:179], v[118:121]
	v_mfma_f32_16x16x32_bf16 v[114:117], v[168:171], v[176:179], v[114:117]
	v_mfma_f32_16x16x32_bf16 v[102:105], v[160:163], v[184:187], v[102:105]
	v_mfma_f32_16x16x32_bf16 v[98:101], v[168:171], v[184:187], v[98:101]
	v_mfma_f32_16x16x32_bf16 v[86:89], v[160:163], v[206:209], v[86:89]
	v_mfma_f32_16x16x32_bf16 v[82:85], v[168:171], v[206:209], v[82:85]
	v_mfma_f32_16x16x32_bf16 v[70:73], v[160:163], v[214:217], v[70:73]
	s_barrier
; #define PG8_STAGE(bufoff, gbase, voff) do { _Pragma("unroll") for (int _i = 0; _i < 2; ++_i) \
;         __builtin_amdgcn_global_load_lds((const unsigned*)((const char*)(gbase) + (voff)[_i]), (LAS unsigned*)(lds + (bufoff) + ldsw + _i * 8192), 16, 0, 0); } while (0)
; #define PG8_LDA(dst, b, h) do { _Pragma("unroll") for (int m = 0; m < 4; ++m) _Pragma("unroll") for (int k = 0; k < 2; ++k) dst[m][k] = *(const LAS bf16x8*)(lds + PG8_SA(b, h) + aoff + m * 2048 + k * 1024); } while (0)
; #define PG8_MMA(ai, bj, At, Bt) do { __builtin_amdgcn_s_setprio(1); _Pragma("unroll") for (int m = 0; m < 4; ++m) _Pragma("unroll") for (int n = 0; n < 2; ++n) _Pragma("unroll") for (int k = 0; k < 2; ++k) \
;         acc[ai][bj][m][n] = __builtin_amdgcn_mfma_f32_16x16x32_bf16(Bt[n][k], At[m][k], acc[ai][bj][m][n], 0, 0, 0); __builtin_amdgcn_s_setprio(0); } while (0)
; #define PG8_WAIT_V(n) asm volatile("s_waitcnt vmcnt(" #n ")" ::: "memory")
; #define PG8_WAIT_L(n) asm volatile("s_waitcnt lgkmcnt(" #n ")" ::: "memory")
; #define PG8_BAR __builtin_amdgcn_s_barrier()
; #define PG8_SCHED __builtin_amdgcn_sched_barrier(0)
; template <class Epi, bool ALIGN_EPI = true, bool SP2 = true>
; __device__ __forceinline__ void gemm_phase(LAS unsigned char* lds, const Gemm g, const StaticOrder& S, const Epi& E, unsigned long long& tacc, const int tmode) {
;     ...
;         for (int t = 0; t < nt; t += 2) {
;             const bool last = (t == nt - 2);
;             const char* a1 = cA + (size_t)(t + 1) * kstepA;
;             const char* a2 = last ? nA : cA + (size_t)(t + 2) * kstepA; const char* b2 = last ? nB : cB + (size_t)(t + 2) * kstepB;
;             const char* a3 = a2 + kstepA; const char* b3 = b2 + kstepB;
;     ...
;             PG8_LDA(At, 1, 1); PG8_STAGE(PG8_SB(1, 0), b3, voffB); PG8_STAGE(PG8_SB(1, 1), b3 + hstepB, voffB); PG8_STAGE(PG8_SA(1, 0), a3, voffA);
;             PG8_WAIT_V(8); PG8_WAIT_L(0); PG8_BAR; PG8_MMA(1, 0, At, B0); PG8_MMA(1, 1, At, B1); PG8_BAR; PG8_SCHED;
	v_mfma_f32_16x16x32_bf16 v[66:69], v[168:171], v[214:217], v[66:69]
	s_setprio 0
	s_add_u32 s0, s40, 0x4000
	s_addc_u32 s1, s41, 0
	s_add_i32 s33, s33, s42
	v_lshl_add_u64 v[138:139], s[0:1], 0, v[130:131]
	s_mov_b32 m0, s33
	ds_read_b128 v[172:175], v142 offset:49152
	ds_read_b128 v[176:179], v142 offset:50176
	ds_read_b128 v[180:183], v142 offset:51200
	ds_read_b128 v[184:187], v142 offset:52224
	ds_read_b128 v[188:191], v142 offset:53248
	ds_read_b128 v[206:209], v142 offset:54272
	ds_read_b128 v[210:213], v142 offset:55296
	ds_read_b128 v[214:217], v142 offset:56320
	global_load_lds_dwordx4 v[138:139], off
	s_add_i32 m0, s33, 0x2000
	v_lshl_add_u64 v[138:139], s[0:1], 0, v[132:133]
	s_add_u32 s0, s40, 0x84000
	s_addc_u32 s1, s41, 0
	s_add_i32 s33, s64, s42
	global_load_lds_dwordx4 v[138:139], off
	v_lshl_add_u64 v[138:139], s[0:1], 0, v[130:131]
	s_mov_b32 m0, s33
	s_nop 0
	global_load_lds_dwordx4 v[138:139], off
	v_lshl_add_u64 v[138:139], s[0:1], 0, v[132:133]
	s_add_i32 m0, s33, 0x2000
	s_nop 0
	global_load_lds_dwordx4 v[138:139], off
	v_lshl_add_u64 v[138:139], s[30:31], 0, v[130:131]
	s_mov_b32 m0, s49
	s_nop 0
	global_load_lds_dwordx4 v[138:139], off
	v_lshl_add_u64 v[138:139], s[30:31], 0, v[132:133]
	s_mov_b32 m0, s50
	s_nop 0
	global_load_lds_dwordx4 v[138:139], off
	s_waitcnt vmcnt(8)
	s_waitcnt lgkmcnt(0)
	s_barrier
	s_setprio 1
	s_waitcnt lgkmcnt(0)
	v_mfma_f32_16x16x32_bf16 v[62:65], v[134:137], v[172:175], v[62:65]
	v_mfma_f32_16x16x32_bf16 v[58:61], v[148:151], v[172:175], v[58:61]
	v_mfma_f32_16x16x32_bf16 v[46:49], v[134:137], v[180:183], v[46:49]
	v_mfma_f32_16x16x32_bf16 v[42:45], v[148:151], v[180:183], v[42:45]
	v_mfma_f32_16x16x32_bf16 v[30:33], v[134:137], v[188:191], v[30:33]
	v_mfma_f32_16x16x32_bf16 v[26:29], v[148:151], v[188:191], v[26:29]
	v_mfma_f32_16x16x32_bf16 v[14:17], v[134:137], v[210:213], v[14:17]
	v_mfma_f32_16x16x32_bf16 v[10:13], v[148:151], v[210:213], v[10:13]
	v_mfma_f32_16x16x32_bf16 v[62:65], v[144:147], v[176:179], v[62:65]
	v_mfma_f32_16x16x32_bf16 v[58:61], v[152:155], v[176:179], v[58:61]
	v_mfma_f32_16x16x32_bf16 v[46:49], v[144:147], v[184:187], v[46:49]
	v_mfma_f32_16x16x32_bf16 v[42:45], v[152:155], v[184:187], v[42:45]
	v_mfma_f32_16x16x32_bf16 v[30:33], v[144:147], v[206:209], v[30:33]
	v_mfma_f32_16x16x32_bf16 v[26:29], v[152:155], v[206:209], v[26:29]
	v_mfma_f32_16x16x32_bf16 v[14:17], v[144:147], v[214:217], v[14:17]
	v_mfma_f32_16x16x32_bf16 v[10:13], v[152:155], v[214:217], v[10:13]
	s_setprio 0
	s_setprio 1
	v_mfma_f32_16x16x32_bf16 v[54:57], v[156:159], v[172:175], v[54:57]
	v_mfma_f32_16x16x32_bf16 v[50:53], v[164:167], v[172:175], v[50:53]
	v_mfma_f32_16x16x32_bf16 v[38:41], v[156:159], v[180:183], v[38:41]
	v_mfma_f32_16x16x32_bf16 v[34:37], v[164:167], v[180:183], v[34:37]
	v_mfma_f32_16x16x32_bf16 v[22:25], v[156:159], v[188:191], v[22:25]
	v_mfma_f32_16x16x32_bf16 v[18:21], v[164:167], v[188:191], v[18:21]
	v_mfma_f32_16x16x32_bf16 v[6:9], v[156:159], v[210:213], v[6:9]
	v_mfma_f32_16x16x32_bf16 v[2:5], v[164:167], v[210:213], v[2:5]
	v_mfma_f32_16x16x32_bf16 v[54:57], v[160:163], v[176:179], v[54:57]
	v_mfma_f32_16x16x32_bf16 v[50:53], v[168:171], v[176:179], v[50:53]
	v_mfma_f32_16x16x32_bf16 v[38:41], v[160:163], v[184:187], v[38:41]
	v_mfma_f32_16x16x32_bf16 v[34:37], v[168:171], v[184:187], v[34:37]
	v_mfma_f32_16x16x32_bf16 v[22:25], v[160:163], v[206:209], v[22:25]
	v_mfma_f32_16x16x32_bf16 v[18:21], v[168:171], v[206:209], v[18:21]
	v_mfma_f32_16x16x32_bf16 v[6:9], v[160:163], v[214:217], v[6:9]
	s_barrier
	v_mfma_f32_16x16x32_bf16 v[2:5], v[168:171], v[214:217], v[2:5]
	s_setprio 0
	s_add_i32 s65, s65, 2
	s_add_u32 s22, s22, 0x8000
	s_addc_u32 s23, s23, 0
	s_add_u32 s60, s60, 0x8000
	s_addc_u32 s61, s61, 0
	s_cmp_lt_u32 s65, 30

; __device__ __forceinline__ const char* b_base(const Gemm& g, const Unit& u) { return (const char*)g.Bt + (size_t)u.pn * 2 * (g.K >> 6) * BLK; }
; #define PG8_STAGE(bufoff, gbase, voff) do { _Pragma("unroll") for (int _i = 0; _i < 2; ++_i) \
;         __builtin_amdgcn_global_load_lds((const unsigned*)((const char*)(gbase) + (voff)[_i]), (LAS unsigned*)(lds + (bufoff) + ldsw + _i * 8192), 16, 0, 0); } while (0)
; #define PG8_LDA(dst, b, h) do { _Pragma("unroll") for (int m = 0; m < 4; ++m) _Pragma("unroll") for (int k = 0; k < 2; ++k) dst[m][k] = *(const LAS bf16x8*)(lds + PG8_SA(b, h) + aoff + m * 2048 + k * 1024); } while (0)
; #define PG8_LDB(dst, b, h) do { _Pragma("unroll") for (int n = 0; n < 2; ++n) _Pragma("unroll") for (int k = 0; k < 2; ++k) dst[n][k] = *(const LAS bf16x8*)(lds + PG8_SB(b, h) + boff + n * 2048 + k * 1024); } while (0)
; #define PG8_BAR __builtin_amdgcn_s_barrier()
; template <class Epi, bool ALIGN_EPI = true, bool SP2 = true>
; __device__ __forceinline__ void gemm_phase(LAS unsigned char* lds, const Gemm g, const StaticOrder& S, const Epi& E, unsigned long long& tacc, const int tmode) {
;     ...
;         const bool has_next = S.next(ui + 1, nxt);
;         const char* nA = has_next ? a_base(g, nxt) : cA; const char* nB = has_next ? b_base(g, nxt) : cB;
;         unsigned long long tk0 = 0ull; if (tmode == 1) tk0 = __builtin_amdgcn_s_memrealtime(); if (tmode == 3) tk0 = (unsigned long long)clock64();
; #pragma unroll 1
;         for (int t = 0; t < nt; t += 2) {
;             const bool last = (t == nt - 2);
;             const char* a1 = cA + (size_t)(t + 1) * kstepA;
;             const char* a2 = last ? nA : cA + (size_t)(t + 2) * kstepA; const char* b2 = last ? nB : cB + (size_t)(t + 2) * kstepB;
;             const char* a3 = a2 + kstepA; const char* b3 = b2 + kstepB;
;             if constexpr (SP2) {
;             PG8_LDB(B0, 0, 0); PG8_LDB(B1, 0, 1); PG8_SCHED; PG8_LDA(At, 0, 0); PG8_STAGE(PG8_SA(1, 1), a1 + hstepA, voffA);
;             PG8_WAIT_V(8); PG8_WAIT_L(0); PG8_BAR; PG8_MMA(0, 0, At, B0); PG8_MMA(0, 1, At, B1); PG8_BAR; PG8_SCHED;
;             PG8_LDA(At, 0, 1); PG8_STAGE(PG8_SB(0, 0), b2, voffB); PG8_STAGE(PG8_SB(0, 1), b2 + hstepB, voffB); PG8_STAGE(PG8_SA(0, 0), a2, voffA);
;             PG8_WAIT_V(8); PG8_WAIT_L(0); PG8_BAR; PG8_MMA(1, 0, At, B0); PG8_MMA(1, 1, At, B1); PG8_BAR; PG8_SCHED;
.LBB0_1153:
	s_ashr_i32 s25, s24, 31
	s_lshl_b64 s[0:1], s[24:25], 20
	s_add_u32 s26, s92, s0
	s_addc_u32 s27, s93, s1
	s_and_b64 s[0:1], s[38:39], exec
	s_cselect_b32 s25, s27, s23
	s_cselect_b32 s55, s26, s22
	s_ashr_i32 s21, s20, 31
	s_lshl_b64 s[0:1], s[20:21], 20
	s_add_u32 s28, s2, s0
	s_addc_u32 s29, s42, s1
	s_and_b64 s[0:1], s[38:39], exec
	s_cselect_b32 s21, s29, s31
	s_cselect_b32 s56, s28, s30
	s_add_u32 s22, s22, 0x84000
	s_addc_u32 s23, s23, 0
	s_add_u32 s57, s30, 0x8000
	v_mov_b32_e32 v2, 0
	s_addc_u32 s60, s31, 0
	s_mov_b32 s61, -2
	s_add_u32 s0, s22, 0xfff84000
	s_addc_u32 s1, s23, -1
	s_cmp_eq_u32 s61, 28
	s_cselect_b32 s34, s55, s0
	s_cselect_b32 s35, s25, s1
	s_cselect_b32 s40, s56, s57
	s_cselect_b32 s41, s21, s60
	s_add_u32 s30, s34, 0x4000
	s_addc_u32 s31, s35, 0
	s_add_i32 s0, 0, 0x10000
	v_add_u32_e32 v130, s0, v137
	s_add_i32 s33, 0, 0x14000
	ds_read_b128 v[140:143], v130
	ds_read_b128 v[144:147], v130 offset:1024
	ds_read_b128 v[148:151], v130 offset:2048
	ds_read_b128 v[152:155], v130 offset:3072
	v_add_u32_e32 v130, s33, v137
	ds_read_b128 v[156:159], v130
	ds_read_b128 v[160:163], v130 offset:1024
	ds_read_b128 v[164:167], v130 offset:2048
	ds_read_b128 v[168:171], v130 offset:3072
	v_lshl_add_u64 v[214:215], s[22:23], 0, v[132:133]
	s_add_i32 m0, s44, 0xc000
	ds_read_b128 v[172:175], v138
	ds_read_b128 v[176:179], v138 offset:1024
	ds_read_b128 v[180:183], v138 offset:2048
	ds_read_b128 v[184:187], v138 offset:3072
	ds_read_b128 v[188:191], v138 offset:4096
	ds_read_b128 v[194:197], v138 offset:5120
	ds_read_b128 v[206:209], v138 offset:6144
	ds_read_b128 v[210:213], v138 offset:7168
	global_load_lds_dwordx4 v[214:215], off
	v_lshl_add_u64 v[214:215], s[22:23], 0, v[134:135]
	s_add_i32 m0, s44, 0xe000
	s_nop 0
	global_load_lds_dwordx4 v[214:215], off
	s_waitcnt vmcnt(8)
	s_waitcnt lgkmcnt(0)
	s_barrier
	s_setprio 1
	s_waitcnt lgkmcnt(0)
	v_mfma_f32_16x16x32_bf16 v[126:129], v[140:143], v[172:175], 0
	v_mfma_f32_16x16x32_bf16 v[122:125], v[148:151], v[172:175], 0
	v_mfma_f32_16x16x32_bf16 v[110:113], v[140:143], v[180:183], 0
	v_mfma_f32_16x16x32_bf16 v[106:109], v[148:151], v[180:183], 0
	v_mfma_f32_16x16x32_bf16 v[94:97], v[140:143], v[188:191], 0
	v_mfma_f32_16x16x32_bf16 v[90:93], v[148:151], v[188:191], 0
	v_mfma_f32_16x16x32_bf16 v[78:81], v[140:143], v[206:209], 0
	v_mfma_f32_16x16x32_bf16 v[74:77], v[148:151], v[206:209], 0
	v_mfma_f32_16x16x32_bf16 v[126:129], v[144:147], v[176:179], v[126:129]
	v_mfma_f32_16x16x32_bf16 v[122:125], v[152:155], v[176:179], v[122:125]
	v_mfma_f32_16x16x32_bf16 v[110:113], v[144:147], v[184:187], v[110:113]
	v_mfma_f32_16x16x32_bf16 v[106:109], v[152:155], v[184:187], v[106:109]
	v_mfma_f32_16x16x32_bf16 v[94:97], v[144:147], v[194:197], v[94:97]
	v_mfma_f32_16x16x32_bf16 v[90:93], v[152:155], v[194:197], v[90:93]
	v_mfma_f32_16x16x32_bf16 v[78:81], v[144:147], v[210:213], v[78:81]
	v_mfma_f32_16x16x32_bf16 v[74:77], v[152:155], v[210:213], v[74:77]
	s_setprio 0
	s_setprio 1
	v_mfma_f32_16x16x32_bf16 v[118:121], v[156:159], v[172:175], 0
	v_mfma_f32_16x16x32_bf16 v[114:117], v[164:167], v[172:175], 0
	v_mfma_f32_16x16x32_bf16 v[102:105], v[156:159], v[180:183], 0
	v_mfma_f32_16x16x32_bf16 v[98:101], v[164:167], v[180:183], 0
	v_mfma_f32_16x16x32_bf16 v[86:89], v[156:159], v[188:191], 0
	v_mfma_f32_16x16x32_bf16 v[82:85], v[164:167], v[188:191], 0
	v_mfma_f32_16x16x32_bf16 v[70:73], v[156:159], v[206:209], 0
	v_mfma_f32_16x16x32_bf16 v[66:69], v[164:167], v[206:209], 0
	v_mfma_f32_16x16x32_bf16 v[118:121], v[160:163], v[176:179], v[118:121]
	v_mfma_f32_16x16x32_bf16 v[114:117], v[168:171], v[176:179], v[114:117]
	v_mfma_f32_16x16x32_bf16 v[102:105], v[160:163], v[184:187], v[102:105]
	v_mfma_f32_16x16x32_bf16 v[98:101], v[168:171], v[184:187], v[98:101]
	v_mfma_f32_16x16x32_bf16 v[86:89], v[160:163], v[194:197], v[86:89]
	v_mfma_f32_16x16x32_bf16 v[82:85], v[168:171], v[194:197], v[82:85]
	v_mfma_f32_16x16x32_bf16 v[70:73], v[160:163], v[210:213], v[70:73]
	s_barrier
	v_mfma_f32_16x16x32_bf16 v[66:69], v[168:171], v[210:213], v[66:69]
	s_setprio 0
	s_add_i32 s0, s0, s43
	v_lshl_add_u64 v[214:215], s[40:41], 0, v[132:133]
	s_mov_b32 m0, s0
	ds_read_b128 v[172:175], v138 offset:16384
	ds_read_b128 v[176:179], v138 offset:17408
	ds_read_b128 v[180:183], v138 offset:18432
	ds_read_b128 v[184:187], v138 offset:19456
	ds_read_b128 v[188:191], v138 offset:20480
	ds_read_b128 v[194:197], v138 offset:21504
	ds_read_b128 v[206:209], v138 offset:22528
	ds_read_b128 v[210:213], v138 offset:23552
	global_load_lds_dwordx4 v[214:215], off
	s_add_i32 m0, s0, 0x2000
	s_add_u32 s0, s40, 0x80000
	v_lshl_add_u64 v[214:215], s[40:41], 0, v[134:135]
	s_addc_u32 s1, s41, 0
	s_add_i32 s33, s33, s43
	global_load_lds_dwordx4 v[214:215], off
	v_lshl_add_u64 v[214:215], s[0:1], 0, v[132:133]
	s_mov_b32 m0, s33
	s_nop 0
	global_load_lds_dwordx4 v[214:215], off
	v_lshl_add_u64 v[214:215], s[0:1], 0, v[134:135]
	s_add_i32 m0, s33, 0x2000
	s_nop 0
	global_load_lds_dwordx4 v[214:215], off
	v_lshl_add_u64 v[214:215], s[34:35], 0, v[132:133]
	s_mov_b32 m0, s44
	s_nop 0
	global_load_lds_dwordx4 v[214:215], off
	v_lshl_add_u64 v[214:215], s[34:35], 0, v[134:135]
	s_mov_b32 m0, s45
	s_nop 0
	global_load_lds_dwordx4 v[214:215], off
	s_waitcnt vmcnt(8)
	s_waitcnt lgkmcnt(0)
	s_barrier
; #define PG8_STAGE(bufoff, gbase, voff) do { _Pragma("unroll") for (int _i = 0; _i < 2; ++_i) \
;         __builtin_amdgcn_global_load_lds((const unsigned*)((const char*)(gbase) + (voff)[_i]), (LAS unsigned*)(lds + (bufoff) + ldsw + _i * 8192), 16, 0, 0); } while (0)
; #define PG8_LDA(dst, b, h) do { _Pragma("unroll") for (int m = 0; m < 4; ++m) _Pragma("unroll") for (int k = 0; k < 2; ++k) dst[m][k] = *(const LAS bf16x8*)(lds + PG8_SA(b, h) + aoff + m * 2048 + k * 1024); } while (0)
; #define PG8_LDB(dst, b, h) do { _Pragma("unroll") for (int n = 0; n < 2; ++n) _Pragma("unroll") for (int k = 0; k < 2; ++k) dst[n][k] = *(const LAS bf16x8*)(lds + PG8_SB(b, h) + boff + n * 2048 + k * 1024); } while (0)
; #define PG8_MMA(ai, bj, At, Bt) do { __builtin_amdgcn_s_setprio(1); _Pragma("unroll") for (int m = 0; m < 4; ++m) _Pragma("unroll") for (int n = 0; n < 2; ++n) _Pragma("unroll") for (int k = 0; k < 2; ++k) \
;         acc[ai][bj][m][n] = __builtin_amdgcn_mfma_f32_16x16x32_bf16(Bt[n][k], At[m][k], acc[ai][bj][m][n], 0, 0, 0); __builtin_amdgcn_s_setprio(0); } while (0)
; #define PG8_WAIT_V(n) asm volatile("s_waitcnt vmcnt(" #n ")" ::: "memory")
; #define PG8_WAIT_L(n) asm volatile("s_waitcnt lgkmcnt(" #n ")" ::: "memory")
; #define PG8_BAR __builtin_amdgcn_s_barrier()
; #define PG8_SCHED __builtin_amdgcn_sched_barrier(0)
; template <class Epi, bool ALIGN_EPI = true, bool SP2 = true>
; __device__ __forceinline__ void gemm_phase(LAS unsigned char* lds, const Gemm g, const StaticOrder& S, const Epi& E, unsigned long long& tacc, const int tmode) {
;     ...
;             PG8_WAIT_V(8); PG8_WAIT_L(0); PG8_BAR; PG8_MMA(1, 0, At, B0); PG8_MMA(1, 1, At, B1); PG8_BAR; PG8_SCHED;
;             PG8_LDB(B0, 1, 0); PG8_LDB(B1, 1, 1); PG8_SCHED; PG8_LDA(At, 1, 0); PG8_STAGE(PG8_SA(0, 1), a2 + hstepA, voffA);
;             PG8_WAIT_V(8); PG8_WAIT_L(0); PG8_BAR; PG8_MMA(0, 0, At, B0); PG8_MMA(0, 1, At, B1); PG8_BAR; PG8_SCHED;
	s_setprio 1
	s_waitcnt lgkmcnt(0)
	v_mfma_f32_16x16x32_bf16 v[62:65], v[140:143], v[172:175], 0
	v_mfma_f32_16x16x32_bf16 v[58:61], v[148:151], v[172:175], 0
	v_mfma_f32_16x16x32_bf16 v[46:49], v[140:143], v[180:183], 0
	v_mfma_f32_16x16x32_bf16 v[42:45], v[148:151], v[180:183], 0
	v_mfma_f32_16x16x32_bf16 v[30:33], v[140:143], v[188:191], 0
	v_mfma_f32_16x16x32_bf16 v[26:29], v[148:151], v[188:191], 0
	v_mfma_f32_16x16x32_bf16 v[14:17], v[140:143], v[206:209], 0
	v_mfma_f32_16x16x32_bf16 v[10:13], v[148:151], v[206:209], 0
	v_mfma_f32_16x16x32_bf16 v[62:65], v[144:147], v[176:179], v[62:65]
	v_mfma_f32_16x16x32_bf16 v[58:61], v[152:155], v[176:179], v[58:61]
	v_mfma_f32_16x16x32_bf16 v[46:49], v[144:147], v[184:187], v[46:49]
	v_mfma_f32_16x16x32_bf16 v[42:45], v[152:155], v[184:187], v[42:45]
	v_mfma_f32_16x16x32_bf16 v[30:33], v[144:147], v[194:197], v[30:33]
	v_mfma_f32_16x16x32_bf16 v[26:29], v[152:155], v[194:197], v[26:29]
	v_mfma_f32_16x16x32_bf16 v[14:17], v[144:147], v[210:213], v[14:17]
	v_mfma_f32_16x16x32_bf16 v[10:13], v[152:155], v[210:213], v[10:13]
	s_setprio 0
	s_setprio 1
	v_mfma_f32_16x16x32_bf16 v[54:57], v[156:159], v[172:175], 0
	v_mfma_f32_16x16x32_bf16 v[50:53], v[164:167], v[172:175], 0
	v_mfma_f32_16x16x32_bf16 v[38:41], v[156:159], v[180:183], 0
	v_mfma_f32_16x16x32_bf16 v[34:37], v[164:167], v[180:183], 0
	v_mfma_f32_16x16x32_bf16 v[22:25], v[156:159], v[188:191], 0
	v_mfma_f32_16x16x32_bf16 v[18:21], v[164:167], v[188:191], 0
	v_mfma_f32_16x16x32_bf16 v[6:9], v[156:159], v[206:209], 0
	v_mfma_f32_16x16x32_bf16 v[2:5], v[164:167], v[206:209], 0
	v_mfma_f32_16x16x32_bf16 v[54:57], v[160:163], v[176:179], v[54:57]
	v_mfma_f32_16x16x32_bf16 v[50:53], v[168:171], v[176:179], v[50:53]
	v_mfma_f32_16x16x32_bf16 v[38:41], v[160:163], v[184:187], v[38:41]
	v_mfma_f32_16x16x32_bf16 v[34:37], v[168:171], v[184:187], v[34:37]
	v_mfma_f32_16x16x32_bf16 v[22:25], v[160:163], v[194:197], v[22:25]
	v_mfma_f32_16x16x32_bf16 v[18:21], v[168:171], v[194:197], v[18:21]
	v_mfma_f32_16x16x32_bf16 v[6:9], v[160:163], v[210:213], v[6:9]
	s_barrier
	v_mfma_f32_16x16x32_bf16 v[2:5], v[168:171], v[210:213], v[2:5]
	s_setprio 0
	s_add_i32 s33, 0, 0x18000
	v_add_u32_e32 v130, s33, v137
	s_add_i32 s64, 0, 0x1c000
	ds_read_b128 v[140:143], v130
	ds_read_b128 v[144:147], v130 offset:1024
	ds_read_b128 v[148:151], v130 offset:2048
	ds_read_b128 v[152:155], v130 offset:3072
	v_add_u32_e32 v130, s64, v137
	ds_read_b128 v[156:159], v130
	ds_read_b128 v[160:163], v130 offset:1024
	ds_read_b128 v[164:167], v130 offset:2048
	ds_read_b128 v[168:171], v130 offset:3072
	s_add_u32 s0, s34, 0x80000
	s_addc_u32 s1, s35, 0
	s_mov_b32 m0, s46
	v_lshl_add_u64 v[214:215], s[0:1], 0, v[132:133]
	ds_read_b128 v[172:175], v138 offset:32768
	ds_read_b128 v[176:179], v138 offset:33792
	ds_read_b128 v[180:183], v138 offset:34816
	ds_read_b128 v[184:187], v138 offset:35840
	ds_read_b128 v[188:191], v138 offset:36864
	ds_read_b128 v[194:197], v138 offset:37888
	ds_read_b128 v[206:209], v138 offset:38912
	ds_read_b128 v[210:213], v138 offset:39936
	global_load_lds_dwordx4 v[214:215], off
	v_lshl_add_u64 v[214:215], s[0:1], 0, v[134:135]
	s_mov_b32 m0, s47
	s_nop 0
	global_load_lds_dwordx4 v[214:215], off
	s_waitcnt vmcnt(8)
	s_waitcnt lgkmcnt(0)
	s_barrier
	s_setprio 1
	s_waitcnt lgkmcnt(0)
	v_mfma_f32_16x16x32_bf16 v[126:129], v[140:143], v[172:175], v[126:129]
	v_mfma_f32_16x16x32_bf16 v[122:125], v[148:151], v[172:175], v[122:125]
	v_mfma_f32_16x16x32_bf16 v[110:113], v[140:143], v[180:183], v[110:113]
	v_mfma_f32_16x16x32_bf16 v[106:109], v[148:151], v[180:183], v[106:109]
	v_mfma_f32_16x16x32_bf16 v[94:97], v[140:143], v[188:191], v[94:97]
	v_mfma_f32_16x16x32_bf16 v[90:93], v[148:151], v[188:191], v[90:93]
	v_mfma_f32_16x16x32_bf16 v[78:81], v[140:143], v[206:209], v[78:81]
	v_mfma_f32_16x16x32_bf16 v[74:77], v[148:151], v[206:209], v[74:77]
	v_mfma_f32_16x16x32_bf16 v[126:129], v[144:147], v[176:179], v[126:129]
	v_mfma_f32_16x16x32_bf16 v[122:125], v[152:155], v[176:179], v[122:125]
	v_mfma_f32_16x16x32_bf16 v[110:113], v[144:147], v[184:187], v[110:113]
	v_mfma_f32_16x16x32_bf16 v[106:109], v[152:155], v[184:187], v[106:109]
	v_mfma_f32_16x16x32_bf16 v[94:97], v[144:147], v[194:197], v[94:97]
	v_mfma_f32_16x16x32_bf16 v[90:93], v[152:155], v[194:197], v[90:93]
	v_mfma_f32_16x16x32_bf16 v[78:81], v[144:147], v[210:213], v[78:81]
	v_mfma_f32_16x16x32_bf16 v[74:77], v[152:155], v[210:213], v[74:77]
	s_setprio 0
	s_setprio 1
	v_mfma_f32_16x16x32_bf16 v[118:121], v[156:159], v[172:175], v[118:121]
	v_mfma_f32_16x16x32_bf16 v[114:117], v[164:167], v[172:175], v[114:117]
	v_mfma_f32_16x16x32_bf16 v[102:105], v[156:159], v[180:183], v[102:105]
	v_mfma_f32_16x16x32_bf16 v[98:101], v[164:167], v[180:183], v[98:101]
	v_mfma_f32_16x16x32_bf16 v[86:89], v[156:159], v[188:191], v[86:89]
	v_mfma_f32_16x16x32_bf16 v[82:85], v[164:167], v[188:191], v[82:85]
	v_mfma_f32_16x16x32_bf16 v[70:73], v[156:159], v[206:209], v[70:73]
	v_mfma_f32_16x16x32_bf16 v[66:69], v[164:167], v[206:209], v[66:69]
	v_mfma_f32_16x16x32_bf16 v[118:121], v[160:163], v[176:179], v[118:121]
	v_mfma_f32_16x16x32_bf16 v[114:117], v[168:171], v[176:179], v[114:117]
	v_mfma_f32_16x16x32_bf16 v[102:105], v[160:163], v[184:187], v[102:105]
	v_mfma_f32_16x16x32_bf16 v[98:101], v[168:171], v[184:187], v[98:101]
	v_mfma_f32_16x16x32_bf16 v[86:89], v[160:163], v[194:197], v[86:89]
	v_mfma_f32_16x16x32_bf16 v[82:85], v[168:171], v[194:197], v[82:85]
	v_mfma_f32_16x16x32_bf16 v[70:73], v[160:163], v[210:213], v[70:73]
	s_barrier
; #define PG8_STAGE(bufoff, gbase, voff) do { _Pragma("unroll") for (int _i = 0; _i < 2; ++_i) \
;         __builtin_amdgcn_global_load_lds((const unsigned*)((const char*)(gbase) + (voff)[_i]), (LAS unsigned*)(lds + (bufoff) + ldsw + _i * 8192), 16, 0, 0); } while (0)
; #define PG8_LDA(dst, b, h) do { _Pragma("unroll") for (int m = 0; m < 4; ++m) _Pragma("unroll") for (int k = 0; k < 2; ++k) dst[m][k] = *(const LAS bf16x8*)(lds + PG8_SA(b, h) + aoff + m * 2048 + k * 1024); } while (0)
; #define PG8_MMA(ai, bj, At, Bt) do { __builtin_amdgcn_s_setprio(1); _Pragma("unroll") for (int m = 0; m < 4; ++m) _Pragma("unroll") for (int n = 0; n < 2; ++n) _Pragma("unroll") for (int k = 0; k < 2; ++k) \
;         acc[ai][bj][m][n] = __builtin_amdgcn_mfma_f32_16x16x32_bf16(Bt[n][k], At[m][k], acc[ai][bj][m][n], 0, 0, 0); __builtin_amdgcn_s_setprio(0); } while (0)
; #define PG8_WAIT_V(n) asm volatile("s_waitcnt vmcnt(" #n ")" ::: "memory")
; #define PG8_WAIT_L(n) asm volatile("s_waitcnt lgkmcnt(" #n ")" ::: "memory")
; #define PG8_BAR __builtin_amdgcn_s_barrier()
; #define PG8_SCHED __builtin_amdgcn_sched_barrier(0)
; template <class Epi, bool ALIGN_EPI = true, bool SP2 = true>
; __device__ __forceinline__ void gemm_phase(LAS unsigned char* lds, const Gemm g, const StaticOrder& S, const Epi& E, unsigned long long& tacc, const int tmode) {
;     ...
;         for (int t = 0; t < nt; t += 2) {
;             const bool last = (t == nt - 2);
;             const char* a1 = cA + (size_t)(t + 1) * kstepA;
;             const char* a2 = last ? nA : cA + (size_t)(t + 2) * kstepA; const char* b2 = last ? nB : cB + (size_t)(t + 2) * kstepB;
;             const char* a3 = a2 + kstepA; const char* b3 = b2 + kstepB;
;     ...
;             PG8_LDA(At, 1, 1); PG8_STAGE(PG8_SB(1, 0), b3, voffB); PG8_STAGE(PG8_SB(1, 1), b3 + hstepB, voffB); PG8_STAGE(PG8_SA(1, 0), a3, voffA);
;             PG8_WAIT_V(8); PG8_WAIT_L(0); PG8_BAR; PG8_MMA(1, 0, At, B0); PG8_MMA(1, 1, At, B1); PG8_BAR; PG8_SCHED;
	v_mfma_f32_16x16x32_bf16 v[66:69], v[168:171], v[210:213], v[66:69]
	s_setprio 0
	s_add_u32 s0, s40, 0x4000
	s_addc_u32 s1, s41, 0
	s_add_i32 s33, s33, s43
	v_lshl_add_u64 v[214:215], s[0:1], 0, v[132:133]
	s_mov_b32 m0, s33
	ds_read_b128 v[172:175], v138 offset:49152
	ds_read_b128 v[176:179], v138 offset:50176
	ds_read_b128 v[180:183], v138 offset:51200
	ds_read_b128 v[184:187], v138 offset:52224
	ds_read_b128 v[188:191], v138 offset:53248
	ds_read_b128 v[194:197], v138 offset:54272
	ds_read_b128 v[206:209], v138 offset:55296
	ds_read_b128 v[210:213], v138 offset:56320
	global_load_lds_dwordx4 v[214:215], off
	s_add_i32 m0, s33, 0x2000
	v_lshl_add_u64 v[214:215], s[0:1], 0, v[134:135]
	s_add_u32 s0, s40, 0x84000
	s_addc_u32 s1, s41, 0
	s_add_i32 s33, s64, s43
	global_load_lds_dwordx4 v[214:215], off
	v_lshl_add_u64 v[214:215], s[0:1], 0, v[132:133]
	s_mov_b32 m0, s33
	s_nop 0
	global_load_lds_dwordx4 v[214:215], off
	v_lshl_add_u64 v[214:215], s[0:1], 0, v[134:135]
	s_add_i32 m0, s33, 0x2000
	s_nop 0
	global_load_lds_dwordx4 v[214:215], off
	v_lshl_add_u64 v[214:215], s[30:31], 0, v[132:133]
	s_mov_b32 m0, s50
	s_nop 0
	global_load_lds_dwordx4 v[214:215], off
	v_lshl_add_u64 v[214:215], s[30:31], 0, v[134:135]
	s_mov_b32 m0, s51
	s_nop 0
	global_load_lds_dwordx4 v[214:215], off
	s_waitcnt vmcnt(8)
	s_waitcnt lgkmcnt(0)
	s_barrier
	s_setprio 1
	s_waitcnt lgkmcnt(0)
	v_mfma_f32_16x16x32_bf16 v[62:65], v[140:143], v[172:175], v[62:65]
	v_mfma_f32_16x16x32_bf16 v[58:61], v[148:151], v[172:175], v[58:61]
	v_mfma_f32_16x16x32_bf16 v[46:49], v[140:143], v[180:183], v[46:49]
	v_mfma_f32_16x16x32_bf16 v[42:45], v[148:151], v[180:183], v[42:45]
	v_mfma_f32_16x16x32_bf16 v[30:33], v[140:143], v[188:191], v[30:33]
	v_mfma_f32_16x16x32_bf16 v[26:29], v[148:151], v[188:191], v[26:29]
	v_mfma_f32_16x16x32_bf16 v[14:17], v[140:143], v[206:209], v[14:17]
	v_mfma_f32_16x16x32_bf16 v[10:13], v[148:151], v[206:209], v[10:13]
	v_mfma_f32_16x16x32_bf16 v[62:65], v[144:147], v[176:179], v[62:65]
	v_mfma_f32_16x16x32_bf16 v[58:61], v[152:155], v[176:179], v[58:61]
	v_mfma_f32_16x16x32_bf16 v[46:49], v[144:147], v[184:187], v[46:49]
	v_mfma_f32_16x16x32_bf16 v[42:45], v[152:155], v[184:187], v[42:45]
	v_mfma_f32_16x16x32_bf16 v[30:33], v[144:147], v[194:197], v[30:33]
	v_mfma_f32_16x16x32_bf16 v[26:29], v[152:155], v[194:197], v[26:29]
	v_mfma_f32_16x16x32_bf16 v[14:17], v[144:147], v[210:213], v[14:17]
	v_mfma_f32_16x16x32_bf16 v[10:13], v[152:155], v[210:213], v[10:13]
	s_setprio 0
	s_setprio 1
	v_mfma_f32_16x16x32_bf16 v[54:57], v[156:159], v[172:175], v[54:57]
	v_mfma_f32_16x16x32_bf16 v[50:53], v[164:167], v[172:175], v[50:53]
	v_mfma_f32_16x16x32_bf16 v[38:41], v[156:159], v[180:183], v[38:41]
	v_mfma_f32_16x16x32_bf16 v[34:37], v[164:167], v[180:183], v[34:37]
	v_mfma_f32_16x16x32_bf16 v[22:25], v[156:159], v[188:191], v[22:25]
	v_mfma_f32_16x16x32_bf16 v[18:21], v[164:167], v[188:191], v[18:21]
	v_mfma_f32_16x16x32_bf16 v[6:9], v[156:159], v[206:209], v[6:9]
	v_mfma_f32_16x16x32_bf16 v[2:5], v[164:167], v[206:209], v[2:5]
	v_mfma_f32_16x16x32_bf16 v[54:57], v[160:163], v[176:179], v[54:57]
	v_mfma_f32_16x16x32_bf16 v[50:53], v[168:171], v[176:179], v[50:53]
	v_mfma_f32_16x16x32_bf16 v[38:41], v[160:163], v[184:187], v[38:41]
	v_mfma_f32_16x16x32_bf16 v[34:37], v[168:171], v[184:187], v[34:37]
	v_mfma_f32_16x16x32_bf16 v[22:25], v[160:163], v[194:197], v[22:25]
	v_mfma_f32_16x16x32_bf16 v[18:21], v[168:171], v[194:197], v[18:21]
	v_mfma_f32_16x16x32_bf16 v[6:9], v[160:163], v[210:213], v[6:9]
	s_barrier
	v_mfma_f32_16x16x32_bf16 v[2:5], v[168:171], v[210:213], v[2:5]
	s_setprio 0
	s_add_i32 s61, s61, 2
	s_add_u32 s22, s22, 0x8000
	s_addc_u32 s23, s23, 0
	s_add_u32 s57, s57, 0x8000
	s_addc_u32 s60, s60, 0
	s_cmp_lt_u32 s61, 30
